# EpiRes residual epilogues: batched base loads with counted vmcnt waits instead of 32-step load-wait-store ladder
# speedup vs baseline: 1.0009x; 1.0009x over previous
; __device__ __forceinline__ unsigned cvt_pk_bf16(float lo, float hi) { unsigned r; asm volatile("v_cvt_pk_bf16_f32 %0, %1, %2" : "=v"(r) : "v"(lo), "v"(hi)); return r; }
;     __device__ __forceinline__ void operator()(const f32x4 (&acc)[2][2][4][2], const Unit& u, int wr, int wc, int fr, int fq) const {
;         int row0 = u.pm * BM + wr * 64 + fr + row_off; const bool isctx = row0 >= NLAT; const int b = isctx ? 8 : (row0 >> 12);
;         const void* bp = isctx ? base_ctx : base_lat; void* op = isctx ? out_ctx : out_lat; if (isctx) row0 -= NLAT;
;         const int col0 = u.pn * BM + wc * 32 + 4 * fq;
;         f32x4 gv[2][2];
; #pragma unroll
;         for (int bj = 0; bj < 2; ++bj)
; #pragma unroll
;             for (int n = 0; n < 2; ++n) gv[bj][n] = *(const f32x4*)(gate + b * MODS + col0 + bj * HALF + n * 16);
; #pragma unroll
;         for (int ai = 0; ai < 2; ++ai)
; #pragma unroll
;             for (int m = 0; m < 4; ++m) { const size_t off = (size_t)(row0 + ai * HALF + m * 16) * DM + col0;
; #pragma unroll
;                 for (int bj = 0; bj < 2; ++bj)
; #pragma unroll
;                     for (int n = 0; n < 2; ++n) { const size_t o2 = off + bj * HALF + n * 16; f32x4 bs;
;                         if (BB) { const u32x2 r = *(const u32x2*)((const bf16_t*)bp + o2); bs = (f32x4){__uint_as_float(r.x << 16), __uint_as_float(r.x & 0xffff0000u), __uint_as_float(r.y << 16), __uint_as_float(r.y & 0xffff0000u)}; }
;                         else bs = *(const f32x4*)((const float*)bp + o2);
;                         const f32x4 o = bs + gv[bj][n] * acc[ai][bj][m][n];
;                         if (OB) { u32x2 w; w.x = cvt_pk_bf16(o[0], o[1]); w.y = cvt_pk_bf16(o[2], o[3]); *(u32x2*)((bf16_t*)op + o2) = w; }
;                         else *(f32x4*)((float*)op + o2) = o; } }
;     }
.LBB0_684:
	s_waitcnt lgkmcnt(0)
	v_lshl_add_u32 v217, s44, 8, v172
	v_lshl_or_b32 v216, s69, 8, v174
	v_lshlrev_b32_e32 v214, 12, v217
	v_lshlrev_b32_e32 v215, 11, v217
	v_lshl_add_u32 v214, v216, 2, v214
	v_lshl_add_u32 v215, v216, 1, v215
	v_add_u32_e32 v215, 0x6000000, v215
	v_mov_b32_e32 v218, s44
	v_lshrrev_b32_e32 v218, 4, v218
	v_mul_u32_u24_e32 v218, 0x1800, v218
	v_add_lshl_u32 v216, v216, v218, 2
	global_load_dwordx4 v[128:131], v216, s[20:21] offset:0
	global_load_dwordx4 v[132:135], v216, s[20:21] offset:64
	global_load_dwordx4 v[136:139], v216, s[20:21] offset:512
	global_load_dwordx4 v[140:143], v216, s[20:21] offset:576
	v_mov_b32_e32 v217, v214
	global_load_dwordx4 v[162:165], v217, s[14:15] offset:0
	global_load_dwordx4 v[166:169], v217, s[14:15] offset:64
	global_load_dwordx4 v[180:183], v217, s[14:15] offset:512
	global_load_dwordx4 v[184:187], v217, s[14:15] offset:576
	v_add_u32_e32 v217, 0x10000, v214
	global_load_dwordx4 v[190:193], v217, s[14:15] offset:0
	global_load_dwordx4 v[194:197], v217, s[14:15] offset:64
	global_load_dwordx4 v[198:201], v217, s[14:15] offset:512
	global_load_dwordx4 v[202:205], v217, s[14:15] offset:576
	v_add_u32_e32 v217, 0x20000, v214
	global_load_dwordx4 v[206:209], v217, s[14:15] offset:0
	global_load_dwordx4 v[210:213], v217, s[14:15] offset:64
	s_waitcnt vmcnt(9)
	v_pk_fma_f32 v[124:125], v[124:125], v[128:129], v[162:163]
	v_pk_fma_f32 v[126:127], v[126:127], v[130:131], v[164:165]
	v_mov_b32_e32 v218, v215
	v_cvt_pk_bf16_f32 v124, v124, v125
	v_cvt_pk_bf16_f32 v125, v126, v127
	global_store_dwordx2 v218, v[124:125], s[4:5] offset:0
	global_load_dwordx4 v[162:165], v217, s[14:15] offset:512
	s_waitcnt vmcnt(10)
	v_pk_fma_f32 v[120:121], v[120:121], v[132:133], v[166:167]
	v_pk_fma_f32 v[122:123], v[122:123], v[134:135], v[168:169]
	v_cvt_pk_bf16_f32 v120, v120, v121
	v_cvt_pk_bf16_f32 v121, v122, v123
	global_store_dwordx2 v218, v[120:121], s[4:5] offset:32
	global_load_dwordx4 v[166:169], v217, s[14:15] offset:576
	v_add_u32_e32 v217, 0x30000, v214
	global_load_dwordx4 v[124:127], v217, s[14:15] offset:0
	s_waitcnt vmcnt(12)
	v_pk_fma_f32 v[116:117], v[116:117], v[136:137], v[180:181]
	v_pk_fma_f32 v[118:119], v[118:119], v[138:139], v[182:183]
	v_cvt_pk_bf16_f32 v116, v116, v117
	v_cvt_pk_bf16_f32 v117, v118, v119
	global_store_dwordx2 v218, v[116:117], s[4:5] offset:256
	global_load_dwordx4 v[180:183], v217, s[14:15] offset:64
	global_load_dwordx4 v[120:123], v217, s[14:15] offset:512
	s_waitcnt vmcnt(14)
	v_pk_fma_f32 v[112:113], v[112:113], v[140:141], v[184:185]
	v_pk_fma_f32 v[114:115], v[114:115], v[142:143], v[186:187]
	v_cvt_pk_bf16_f32 v112, v112, v113
	v_cvt_pk_bf16_f32 v113, v114, v115
	global_store_dwordx2 v218, v[112:113], s[4:5] offset:288
	global_load_dwordx4 v[184:187], v217, s[14:15] offset:576
	v_add_u32_e32 v217, 0x80000, v214
	global_load_dwordx4 v[116:119], v217, s[14:15] offset:0
	s_waitcnt vmcnt(16)
	v_pk_fma_f32 v[108:109], v[108:109], v[128:129], v[190:191]
	v_pk_fma_f32 v[110:111], v[110:111], v[130:131], v[192:193]
	v_add_u32_e32 v218, 0x8000, v215
	v_cvt_pk_bf16_f32 v108, v108, v109
	v_cvt_pk_bf16_f32 v109, v110, v111
	global_store_dwordx2 v218, v[108:109], s[4:5] offset:0
	global_load_dwordx4 v[190:193], v217, s[14:15] offset:64
	global_load_dwordx4 v[112:115], v217, s[14:15] offset:512
	s_waitcnt vmcnt(18)
	v_pk_fma_f32 v[104:105], v[104:105], v[132:133], v[194:195]
	v_pk_fma_f32 v[106:107], v[106:107], v[134:135], v[196:197]
	v_cvt_pk_bf16_f32 v104, v104, v105
	v_cvt_pk_bf16_f32 v105, v106, v107
	global_store_dwordx2 v218, v[104:105], s[4:5] offset:32
	global_load_dwordx4 v[194:197], v217, s[14:15] offset:576
	v_add_u32_e32 v217, 0x90000, v214
	global_load_dwordx4 v[108:111], v217, s[14:15] offset:0
	s_waitcnt vmcnt(20)
	v_pk_fma_f32 v[100:101], v[100:101], v[136:137], v[198:199]
	v_pk_fma_f32 v[102:103], v[102:103], v[138:139], v[200:201]
	v_cvt_pk_bf16_f32 v100, v100, v101
	v_cvt_pk_bf16_f32 v101, v102, v103
	global_store_dwordx2 v218, v[100:101], s[4:5] offset:256
	global_load_dwordx4 v[198:201], v217, s[14:15] offset:64
	global_load_dwordx4 v[104:107], v217, s[14:15] offset:512
	s_waitcnt vmcnt(22)
	v_pk_fma_f32 v[96:97], v[96:97], v[140:141], v[202:203]
	v_pk_fma_f32 v[98:99], v[98:99], v[142:143], v[204:205]
	v_cvt_pk_bf16_f32 v96, v96, v97
	v_cvt_pk_bf16_f32 v97, v98, v99
	global_store_dwordx2 v218, v[96:97], s[4:5] offset:288
	global_load_dwordx4 v[202:205], v217, s[14:15] offset:576
	v_add_u32_e32 v217, 0xa0000, v214
	global_load_dwordx4 v[100:103], v217, s[14:15] offset:0
	s_waitcnt vmcnt(24)
	v_pk_fma_f32 v[92:93], v[92:93], v[128:129], v[206:207]
	v_pk_fma_f32 v[94:95], v[94:95], v[130:131], v[208:209]
	v_add_u32_e32 v218, 0x10000, v215
	v_cvt_pk_bf16_f32 v92, v92, v93
	v_cvt_pk_bf16_f32 v93, v94, v95
	global_store_dwordx2 v218, v[92:93], s[4:5] offset:0
	global_load_dwordx4 v[206:209], v217, s[14:15] offset:64
	global_load_dwordx4 v[96:99], v217, s[14:15] offset:512
	s_waitcnt vmcnt(26)
	v_pk_fma_f32 v[88:89], v[88:89], v[132:133], v[210:211]
	v_pk_fma_f32 v[90:91], v[90:91], v[134:135], v[212:213]
	v_cvt_pk_bf16_f32 v88, v88, v89
	v_cvt_pk_bf16_f32 v89, v90, v91
	global_store_dwordx2 v218, v[88:89], s[4:5] offset:32
	global_load_dwordx4 v[210:213], v217, s[14:15] offset:576
	v_add_u32_e32 v217, 0xb0000, v214
	global_load_dwordx4 v[92:95], v217, s[14:15] offset:0
	s_waitcnt vmcnt(27)
	v_pk_fma_f32 v[84:85], v[84:85], v[136:137], v[162:163]
	v_pk_fma_f32 v[86:87], v[86:87], v[138:139], v[164:165]
	v_cvt_pk_bf16_f32 v84, v84, v85
	v_cvt_pk_bf16_f32 v85, v86, v87
	global_store_dwordx2 v218, v[84:85], s[4:5] offset:256
	global_load_dwordx4 v[162:165], v217, s[14:15] offset:64
	global_load_dwordx4 v[88:91], v217, s[14:15] offset:512
	s_waitcnt vmcnt(28)
; __device__ __forceinline__ unsigned cvt_pk_bf16(float lo, float hi) { unsigned r; asm volatile("v_cvt_pk_bf16_f32 %0, %1, %2" : "=v"(r) : "v"(lo), "v"(hi)); return r; }
;     __device__ __forceinline__ void operator()(const f32x4 (&acc)[2][2][4][2], const Unit& u, int wr, int wc, int fr, int fq) const {
;         int row0 = u.pm * BM + wr * 64 + fr + row_off; const bool isctx = row0 >= NLAT; const int b = isctx ? 8 : (row0 >> 12);
;         const void* bp = isctx ? base_ctx : base_lat; void* op = isctx ? out_ctx : out_lat; if (isctx) row0 -= NLAT;
;         const int col0 = u.pn * BM + wc * 32 + 4 * fq;
;         f32x4 gv[2][2];
; #pragma unroll
;         for (int bj = 0; bj < 2; ++bj)
; #pragma unroll
;             for (int n = 0; n < 2; ++n) gv[bj][n] = *(const f32x4*)(gate + b * MODS + col0 + bj * HALF + n * 16);
; #pragma unroll
;         for (int ai = 0; ai < 2; ++ai)
; #pragma unroll
;             for (int m = 0; m < 4; ++m) { const size_t off = (size_t)(row0 + ai * HALF + m * 16) * DM + col0;
; #pragma unroll
;                 for (int bj = 0; bj < 2; ++bj)
; #pragma unroll
;                     for (int n = 0; n < 2; ++n) { const size_t o2 = off + bj * HALF + n * 16; f32x4 bs;
;                         if (BB) { const u32x2 r = *(const u32x2*)((const bf16_t*)bp + o2); bs = (f32x4){__uint_as_float(r.x << 16), __uint_as_float(r.x & 0xffff0000u), __uint_as_float(r.y << 16), __uint_as_float(r.y & 0xffff0000u)}; }
;                         else bs = *(const f32x4*)((const float*)bp + o2);
;                         const f32x4 o = bs + gv[bj][n] * acc[ai][bj][m][n];
;                         if (OB) { u32x2 w; w.x = cvt_pk_bf16(o[0], o[1]); w.y = cvt_pk_bf16(o[2], o[3]); *(u32x2*)((bf16_t*)op + o2) = w; }
;                         else *(f32x4*)((float*)op + o2) = o; } }
;     }
	v_pk_fma_f32 v[80:81], v[80:81], v[140:141], v[166:167]
	v_pk_fma_f32 v[82:83], v[82:83], v[142:143], v[168:169]
	v_cvt_pk_bf16_f32 v80, v80, v81
	v_cvt_pk_bf16_f32 v81, v82, v83
	global_store_dwordx2 v218, v[80:81], s[4:5] offset:288
	global_load_dwordx4 v[166:169], v217, s[14:15] offset:576
	s_waitcnt vmcnt(29)
	v_pk_fma_f32 v[76:77], v[76:77], v[128:129], v[124:125]
	v_pk_fma_f32 v[78:79], v[78:79], v[130:131], v[126:127]
	v_add_u32_e32 v218, 0x18000, v215
	v_cvt_pk_bf16_f32 v76, v76, v77
	v_cvt_pk_bf16_f32 v77, v78, v79
	global_store_dwordx2 v218, v[76:77], s[4:5] offset:0
	s_waitcnt vmcnt(28)
	v_pk_fma_f32 v[72:73], v[72:73], v[132:133], v[180:181]
	v_pk_fma_f32 v[74:75], v[74:75], v[134:135], v[182:183]
	v_cvt_pk_bf16_f32 v72, v72, v73
	v_cvt_pk_bf16_f32 v73, v74, v75
	global_store_dwordx2 v218, v[72:73], s[4:5] offset:32
	s_waitcnt vmcnt(28)
	v_pk_fma_f32 v[68:69], v[68:69], v[136:137], v[120:121]
	v_pk_fma_f32 v[70:71], v[70:71], v[138:139], v[122:123]
	v_cvt_pk_bf16_f32 v68, v68, v69
	v_cvt_pk_bf16_f32 v69, v70, v71
	global_store_dwordx2 v218, v[68:69], s[4:5] offset:256
	s_waitcnt vmcnt(27)
	v_pk_fma_f32 v[64:65], v[64:65], v[140:141], v[184:185]
	v_pk_fma_f32 v[66:67], v[66:67], v[142:143], v[186:187]
	v_cvt_pk_bf16_f32 v64, v64, v65
	v_cvt_pk_bf16_f32 v65, v66, v67
	global_store_dwordx2 v218, v[64:65], s[4:5] offset:288
	s_waitcnt vmcnt(27)
	v_pk_fma_f32 v[60:61], v[60:61], v[128:129], v[116:117]
	v_pk_fma_f32 v[62:63], v[62:63], v[130:131], v[118:119]
	v_add_u32_e32 v218, 0x40000, v215
	v_cvt_pk_bf16_f32 v60, v60, v61
	v_cvt_pk_bf16_f32 v61, v62, v63
	global_store_dwordx2 v218, v[60:61], s[4:5] offset:0
	s_waitcnt vmcnt(26)
	v_pk_fma_f32 v[56:57], v[56:57], v[132:133], v[190:191]
	v_pk_fma_f32 v[58:59], v[58:59], v[134:135], v[192:193]
	v_cvt_pk_bf16_f32 v56, v56, v57
	v_cvt_pk_bf16_f32 v57, v58, v59
	global_store_dwordx2 v218, v[56:57], s[4:5] offset:32
	s_waitcnt vmcnt(26)
	v_pk_fma_f32 v[52:53], v[52:53], v[136:137], v[112:113]
	v_pk_fma_f32 v[54:55], v[54:55], v[138:139], v[114:115]
	v_cvt_pk_bf16_f32 v52, v52, v53
	v_cvt_pk_bf16_f32 v53, v54, v55
	global_store_dwordx2 v218, v[52:53], s[4:5] offset:256
	s_waitcnt vmcnt(25)
	v_pk_fma_f32 v[48:49], v[48:49], v[140:141], v[194:195]
	v_pk_fma_f32 v[50:51], v[50:51], v[142:143], v[196:197]
	v_cvt_pk_bf16_f32 v48, v48, v49
	v_cvt_pk_bf16_f32 v49, v50, v51
	global_store_dwordx2 v218, v[48:49], s[4:5] offset:288
	s_waitcnt vmcnt(25)
	v_pk_fma_f32 v[44:45], v[44:45], v[128:129], v[108:109]
	v_pk_fma_f32 v[46:47], v[46:47], v[130:131], v[110:111]
	v_add_u32_e32 v218, 0x48000, v215
	v_cvt_pk_bf16_f32 v44, v44, v45
	v_cvt_pk_bf16_f32 v45, v46, v47
	global_store_dwordx2 v218, v[44:45], s[4:5] offset:0
	s_waitcnt vmcnt(24)
	v_pk_fma_f32 v[40:41], v[40:41], v[132:133], v[198:199]
	v_pk_fma_f32 v[42:43], v[42:43], v[134:135], v[200:201]
	v_cvt_pk_bf16_f32 v40, v40, v41
	v_cvt_pk_bf16_f32 v41, v42, v43
	global_store_dwordx2 v218, v[40:41], s[4:5] offset:32
	s_waitcnt vmcnt(24)
	v_pk_fma_f32 v[36:37], v[36:37], v[136:137], v[104:105]
	v_pk_fma_f32 v[38:39], v[38:39], v[138:139], v[106:107]
	v_cvt_pk_bf16_f32 v36, v36, v37
	v_cvt_pk_bf16_f32 v37, v38, v39
	global_store_dwordx2 v218, v[36:37], s[4:5] offset:256
	s_waitcnt vmcnt(23)
	v_pk_fma_f32 v[32:33], v[32:33], v[140:141], v[202:203]
	v_pk_fma_f32 v[34:35], v[34:35], v[142:143], v[204:205]
	v_cvt_pk_bf16_f32 v32, v32, v33
	v_cvt_pk_bf16_f32 v33, v34, v35
	global_store_dwordx2 v218, v[32:33], s[4:5] offset:288
	s_waitcnt vmcnt(23)
	v_pk_fma_f32 v[28:29], v[28:29], v[128:129], v[100:101]
	v_pk_fma_f32 v[30:31], v[30:31], v[130:131], v[102:103]
	v_add_u32_e32 v218, 0x50000, v215
	v_cvt_pk_bf16_f32 v28, v28, v29
	v_cvt_pk_bf16_f32 v29, v30, v31
	global_store_dwordx2 v218, v[28:29], s[4:5] offset:0
	s_waitcnt vmcnt(22)
	v_pk_fma_f32 v[24:25], v[24:25], v[132:133], v[206:207]
	v_pk_fma_f32 v[26:27], v[26:27], v[134:135], v[208:209]
	v_cvt_pk_bf16_f32 v24, v24, v25
	v_cvt_pk_bf16_f32 v25, v26, v27
	global_store_dwordx2 v218, v[24:25], s[4:5] offset:32
	s_waitcnt vmcnt(22)
	v_pk_fma_f32 v[20:21], v[20:21], v[136:137], v[96:97]
	v_pk_fma_f32 v[22:23], v[22:23], v[138:139], v[98:99]
	v_cvt_pk_bf16_f32 v20, v20, v21
	v_cvt_pk_bf16_f32 v21, v22, v23
	global_store_dwordx2 v218, v[20:21], s[4:5] offset:256
	s_waitcnt vmcnt(21)
	v_pk_fma_f32 v[16:17], v[16:17], v[140:141], v[210:211]
	v_pk_fma_f32 v[18:19], v[18:19], v[142:143], v[212:213]
	v_cvt_pk_bf16_f32 v16, v16, v17
	v_cvt_pk_bf16_f32 v17, v18, v19
	global_store_dwordx2 v218, v[16:17], s[4:5] offset:288
	s_waitcnt vmcnt(21)
	v_pk_fma_f32 v[12:13], v[12:13], v[128:129], v[92:93]
	v_pk_fma_f32 v[14:15], v[14:15], v[130:131], v[94:95]
	v_add_u32_e32 v218, 0x58000, v215
	v_cvt_pk_bf16_f32 v12, v12, v13
	v_cvt_pk_bf16_f32 v13, v14, v15
	global_store_dwordx2 v218, v[12:13], s[4:5] offset:0
	s_waitcnt vmcnt(20)
	v_pk_fma_f32 v[8:9], v[8:9], v[132:133], v[162:163]
	v_pk_fma_f32 v[10:11], v[10:11], v[134:135], v[164:165]
	v_cvt_pk_bf16_f32 v8, v8, v9
	v_cvt_pk_bf16_f32 v9, v10, v11
	global_store_dwordx2 v218, v[8:9], s[4:5] offset:32
	s_waitcnt vmcnt(20)
	v_pk_fma_f32 v[4:5], v[4:5], v[136:137], v[88:89]
	v_pk_fma_f32 v[6:7], v[6:7], v[138:139], v[90:91]
	v_cvt_pk_bf16_f32 v4, v4, v5
	v_cvt_pk_bf16_f32 v5, v6, v7
	global_store_dwordx2 v218, v[4:5], s[4:5] offset:256
	s_waitcnt vmcnt(19)
	v_pk_fma_f32 v[0:1], v[0:1], v[140:141], v[166:167]
	v_pk_fma_f32 v[2:3], v[2:3], v[142:143], v[168:169]
	v_cvt_pk_bf16_f32 v0, v0, v1
	v_cvt_pk_bf16_f32 v1, v2, v3
	global_store_dwordx2 v218, v[0:1], s[4:5] offset:288
	s_and_b64 vcc, exec, s[6:7]
	s_mov_b64 s[6:7], -1
	s_cbranch_vccnz .LBB0_670
	s_andn2_b64 vcc, exec, s[18:19]
	s_cbranch_vccnz .LBB0_669
	s_barrier
	s_branch .LBB0_669

; __device__ __forceinline__ unsigned cvt_pk_bf16(float lo, float hi) { unsigned r; asm volatile("v_cvt_pk_bf16_f32 %0, %1, %2" : "=v"(r) : "v"(lo), "v"(hi)); return r; }
;     __device__ __forceinline__ void operator()(const f32x4 (&acc)[2][2][4][2], const Unit& u, int wr, int wc, int fr, int fq) const {
;         int row0 = u.pm * BM + wr * 64 + fr + row_off; const bool isctx = row0 >= NLAT; const int b = isctx ? 8 : (row0 >> 12);
;         const void* bp = isctx ? base_ctx : base_lat; void* op = isctx ? out_ctx : out_lat; if (isctx) row0 -= NLAT;
;         const int col0 = u.pn * BM + wc * 32 + 4 * fq;
;         f32x4 gv[2][2];
; #pragma unroll
;         for (int bj = 0; bj < 2; ++bj)
; #pragma unroll
;             for (int n = 0; n < 2; ++n) gv[bj][n] = *(const f32x4*)(gate + b * MODS + col0 + bj * HALF + n * 16);
; #pragma unroll
;         for (int ai = 0; ai < 2; ++ai)
; #pragma unroll
;             for (int m = 0; m < 4; ++m) { const size_t off = (size_t)(row0 + ai * HALF + m * 16) * DM + col0;
; #pragma unroll
;                 for (int bj = 0; bj < 2; ++bj)
; #pragma unroll
;                     for (int n = 0; n < 2; ++n) { const size_t o2 = off + bj * HALF + n * 16; f32x4 bs;
;                         if (BB) { const u32x2 r = *(const u32x2*)((const bf16_t*)bp + o2); bs = (f32x4){__uint_as_float(r.x << 16), __uint_as_float(r.x & 0xffff0000u), __uint_as_float(r.y << 16), __uint_as_float(r.y & 0xffff0000u)}; }
;                         else bs = *(const f32x4*)((const float*)bp + o2);
;                         const f32x4 o = bs + gv[bj][n] * acc[ai][bj][m][n];
;                         if (OB) { u32x2 w; w.x = cvt_pk_bf16(o[0], o[1]); w.y = cvt_pk_bf16(o[2], o[3]); *(u32x2*)((bf16_t*)op + o2) = w; }
;                         else *(f32x4*)((float*)op + o2) = o; } }
;     }
.LBB0_765:
	s_waitcnt lgkmcnt(0)
	v_lshl_add_u32 v209, s42, 8, v166
	v_lshl_or_b32 v208, s74, 8, v168
	v_lshlrev_b32_e32 v206, 12, v209
	v_lshlrev_b32_e32 v207, 11, v209
	v_lshl_add_u32 v206, v208, 2, v206
	v_lshl_add_u32 v207, v208, 1, v207
	v_add_u32_e32 v207, 0x4000000, v207
	v_lshlrev_b32_e32 v208, 2, v208
	v_add_u32_e32 v208, 0x30000, v208
	global_load_dwordx4 v[128:131], v208, s[18:19] offset:0
	global_load_dwordx4 v[132:135], v208, s[18:19] offset:64
	global_load_dwordx4 v[136:139], v208, s[18:19] offset:512
	global_load_dwordx4 v[140:143], v208, s[18:19] offset:576
	v_mov_b32_e32 v209, v206
	global_load_dwordx4 v[156:159], v209, s[14:15] offset:0
	global_load_dwordx4 v[160:163], v209, s[14:15] offset:64
	global_load_dwordx4 v[172:175], v209, s[14:15] offset:512
	global_load_dwordx4 v[176:179], v209, s[14:15] offset:576
	v_add_u32_e32 v209, 0x10000, v206
	global_load_dwordx4 v[180:183], v209, s[14:15] offset:0
	global_load_dwordx4 v[184:187], v209, s[14:15] offset:64
	global_load_dwordx4 v[190:193], v209, s[14:15] offset:512
	global_load_dwordx4 v[194:197], v209, s[14:15] offset:576
	v_add_u32_e32 v209, 0x20000, v206
	global_load_dwordx4 v[198:201], v209, s[14:15] offset:0
	global_load_dwordx4 v[202:205], v209, s[14:15] offset:64
	s_waitcnt vmcnt(9)
	v_pk_fma_f32 v[124:125], v[124:125], v[128:129], v[156:157]
	v_pk_fma_f32 v[126:127], v[126:127], v[130:131], v[158:159]
	v_mov_b32_e32 v210, v207
	v_cvt_pk_bf16_f32 v124, v124, v125
	v_cvt_pk_bf16_f32 v125, v126, v127
	global_store_dwordx2 v210, v[124:125], s[52:53] offset:0
	global_load_dwordx4 v[156:159], v209, s[14:15] offset:512
	s_waitcnt vmcnt(10)
	v_pk_fma_f32 v[120:121], v[120:121], v[132:133], v[160:161]
	v_pk_fma_f32 v[122:123], v[122:123], v[134:135], v[162:163]
	v_cvt_pk_bf16_f32 v120, v120, v121
	v_cvt_pk_bf16_f32 v121, v122, v123
	global_store_dwordx2 v210, v[120:121], s[52:53] offset:32
	global_load_dwordx4 v[160:163], v209, s[14:15] offset:576
	v_add_u32_e32 v209, 0x30000, v206
	global_load_dwordx4 v[124:127], v209, s[14:15] offset:0
	s_waitcnt vmcnt(12)
	v_pk_fma_f32 v[116:117], v[116:117], v[136:137], v[172:173]
	v_pk_fma_f32 v[118:119], v[118:119], v[138:139], v[174:175]
	v_cvt_pk_bf16_f32 v116, v116, v117
	v_cvt_pk_bf16_f32 v117, v118, v119
	global_store_dwordx2 v210, v[116:117], s[52:53] offset:256
	global_load_dwordx4 v[172:175], v209, s[14:15] offset:64
	global_load_dwordx4 v[120:123], v209, s[14:15] offset:512
	s_waitcnt vmcnt(14)
	v_pk_fma_f32 v[112:113], v[112:113], v[140:141], v[176:177]
	v_pk_fma_f32 v[114:115], v[114:115], v[142:143], v[178:179]
	v_cvt_pk_bf16_f32 v112, v112, v113
	v_cvt_pk_bf16_f32 v113, v114, v115
	global_store_dwordx2 v210, v[112:113], s[52:53] offset:288
	global_load_dwordx4 v[176:179], v209, s[14:15] offset:576
	v_add_u32_e32 v209, 0x80000, v206
	global_load_dwordx4 v[116:119], v209, s[14:15] offset:0
	s_waitcnt vmcnt(16)
	v_pk_fma_f32 v[108:109], v[108:109], v[128:129], v[180:181]
	v_pk_fma_f32 v[110:111], v[110:111], v[130:131], v[182:183]
	v_add_u32_e32 v210, 0x8000, v207
	v_cvt_pk_bf16_f32 v108, v108, v109
	v_cvt_pk_bf16_f32 v109, v110, v111
	global_store_dwordx2 v210, v[108:109], s[52:53] offset:0
	global_load_dwordx4 v[180:183], v209, s[14:15] offset:64
	global_load_dwordx4 v[112:115], v209, s[14:15] offset:512
	s_waitcnt vmcnt(18)
	v_pk_fma_f32 v[104:105], v[104:105], v[132:133], v[184:185]
	v_pk_fma_f32 v[106:107], v[106:107], v[134:135], v[186:187]
	v_cvt_pk_bf16_f32 v104, v104, v105
	v_cvt_pk_bf16_f32 v105, v106, v107
	global_store_dwordx2 v210, v[104:105], s[52:53] offset:32
	global_load_dwordx4 v[184:187], v209, s[14:15] offset:576
	v_add_u32_e32 v209, 0x90000, v206
	global_load_dwordx4 v[108:111], v209, s[14:15] offset:0
	s_waitcnt vmcnt(20)
	v_pk_fma_f32 v[100:101], v[100:101], v[136:137], v[190:191]
	v_pk_fma_f32 v[102:103], v[102:103], v[138:139], v[192:193]
	v_cvt_pk_bf16_f32 v100, v100, v101
	v_cvt_pk_bf16_f32 v101, v102, v103
	global_store_dwordx2 v210, v[100:101], s[52:53] offset:256
	global_load_dwordx4 v[190:193], v209, s[14:15] offset:64
	global_load_dwordx4 v[104:107], v209, s[14:15] offset:512
	s_waitcnt vmcnt(22)
	v_pk_fma_f32 v[96:97], v[96:97], v[140:141], v[194:195]
	v_pk_fma_f32 v[98:99], v[98:99], v[142:143], v[196:197]
	v_cvt_pk_bf16_f32 v96, v96, v97
	v_cvt_pk_bf16_f32 v97, v98, v99
	global_store_dwordx2 v210, v[96:97], s[52:53] offset:288
	global_load_dwordx4 v[194:197], v209, s[14:15] offset:576
	v_add_u32_e32 v209, 0xa0000, v206
	global_load_dwordx4 v[100:103], v209, s[14:15] offset:0
	s_waitcnt vmcnt(24)
	v_pk_fma_f32 v[92:93], v[92:93], v[128:129], v[198:199]
	v_pk_fma_f32 v[94:95], v[94:95], v[130:131], v[200:201]
	v_add_u32_e32 v210, 0x10000, v207
	v_cvt_pk_bf16_f32 v92, v92, v93
	v_cvt_pk_bf16_f32 v93, v94, v95
	global_store_dwordx2 v210, v[92:93], s[52:53] offset:0
	global_load_dwordx4 v[198:201], v209, s[14:15] offset:64
	global_load_dwordx4 v[96:99], v209, s[14:15] offset:512
	s_waitcnt vmcnt(26)
	v_pk_fma_f32 v[88:89], v[88:89], v[132:133], v[202:203]
	v_pk_fma_f32 v[90:91], v[90:91], v[134:135], v[204:205]
	v_cvt_pk_bf16_f32 v88, v88, v89
	v_cvt_pk_bf16_f32 v89, v90, v91
	global_store_dwordx2 v210, v[88:89], s[52:53] offset:32
	global_load_dwordx4 v[202:205], v209, s[14:15] offset:576
	v_add_u32_e32 v209, 0xb0000, v206
	global_load_dwordx4 v[92:95], v209, s[14:15] offset:0
	s_waitcnt vmcnt(27)
	v_pk_fma_f32 v[84:85], v[84:85], v[136:137], v[156:157]
	v_pk_fma_f32 v[86:87], v[86:87], v[138:139], v[158:159]
	v_cvt_pk_bf16_f32 v84, v84, v85
	v_cvt_pk_bf16_f32 v85, v86, v87
	global_store_dwordx2 v210, v[84:85], s[52:53] offset:256
	global_load_dwordx4 v[156:159], v209, s[14:15] offset:64
	global_load_dwordx4 v[88:91], v209, s[14:15] offset:512
	s_waitcnt vmcnt(28)
; __device__ __forceinline__ unsigned cvt_pk_bf16(float lo, float hi) { unsigned r; asm volatile("v_cvt_pk_bf16_f32 %0, %1, %2" : "=v"(r) : "v"(lo), "v"(hi)); return r; }
;     __device__ __forceinline__ void operator()(const f32x4 (&acc)[2][2][4][2], const Unit& u, int wr, int wc, int fr, int fq) const {
;         int row0 = u.pm * BM + wr * 64 + fr + row_off; const bool isctx = row0 >= NLAT; const int b = isctx ? 8 : (row0 >> 12);
;         const void* bp = isctx ? base_ctx : base_lat; void* op = isctx ? out_ctx : out_lat; if (isctx) row0 -= NLAT;
;         const int col0 = u.pn * BM + wc * 32 + 4 * fq;
;         f32x4 gv[2][2];
; #pragma unroll
;         for (int bj = 0; bj < 2; ++bj)
; #pragma unroll
;             for (int n = 0; n < 2; ++n) gv[bj][n] = *(const f32x4*)(gate + b * MODS + col0 + bj * HALF + n * 16);
; #pragma unroll
;         for (int ai = 0; ai < 2; ++ai)
; #pragma unroll
;             for (int m = 0; m < 4; ++m) { const size_t off = (size_t)(row0 + ai * HALF + m * 16) * DM + col0;
; #pragma unroll
;                 for (int bj = 0; bj < 2; ++bj)
; #pragma unroll
;                     for (int n = 0; n < 2; ++n) { const size_t o2 = off + bj * HALF + n * 16; f32x4 bs;
;                         if (BB) { const u32x2 r = *(const u32x2*)((const bf16_t*)bp + o2); bs = (f32x4){__uint_as_float(r.x << 16), __uint_as_float(r.x & 0xffff0000u), __uint_as_float(r.y << 16), __uint_as_float(r.y & 0xffff0000u)}; }
;                         else bs = *(const f32x4*)((const float*)bp + o2);
;                         const f32x4 o = bs + gv[bj][n] * acc[ai][bj][m][n];
;                         if (OB) { u32x2 w; w.x = cvt_pk_bf16(o[0], o[1]); w.y = cvt_pk_bf16(o[2], o[3]); *(u32x2*)((bf16_t*)op + o2) = w; }
;                         else *(f32x4*)((float*)op + o2) = o; } }
;     }
	v_pk_fma_f32 v[80:81], v[80:81], v[140:141], v[160:161]
	v_pk_fma_f32 v[82:83], v[82:83], v[142:143], v[162:163]
	v_cvt_pk_bf16_f32 v80, v80, v81
	v_cvt_pk_bf16_f32 v81, v82, v83
	global_store_dwordx2 v210, v[80:81], s[52:53] offset:288
	global_load_dwordx4 v[160:163], v209, s[14:15] offset:576
	s_waitcnt vmcnt(29)
	v_pk_fma_f32 v[76:77], v[76:77], v[128:129], v[124:125]
	v_pk_fma_f32 v[78:79], v[78:79], v[130:131], v[126:127]
	v_add_u32_e32 v210, 0x18000, v207
	v_cvt_pk_bf16_f32 v76, v76, v77
	v_cvt_pk_bf16_f32 v77, v78, v79
	global_store_dwordx2 v210, v[76:77], s[52:53] offset:0
	s_waitcnt vmcnt(28)
	v_pk_fma_f32 v[72:73], v[72:73], v[132:133], v[172:173]
	v_pk_fma_f32 v[74:75], v[74:75], v[134:135], v[174:175]
	v_cvt_pk_bf16_f32 v72, v72, v73
	v_cvt_pk_bf16_f32 v73, v74, v75
	global_store_dwordx2 v210, v[72:73], s[52:53] offset:32
	s_waitcnt vmcnt(28)
	v_pk_fma_f32 v[68:69], v[68:69], v[136:137], v[120:121]
	v_pk_fma_f32 v[70:71], v[70:71], v[138:139], v[122:123]
	v_cvt_pk_bf16_f32 v68, v68, v69
	v_cvt_pk_bf16_f32 v69, v70, v71
	global_store_dwordx2 v210, v[68:69], s[52:53] offset:256
	s_waitcnt vmcnt(27)
	v_pk_fma_f32 v[64:65], v[64:65], v[140:141], v[176:177]
	v_pk_fma_f32 v[66:67], v[66:67], v[142:143], v[178:179]
	v_cvt_pk_bf16_f32 v64, v64, v65
	v_cvt_pk_bf16_f32 v65, v66, v67
	global_store_dwordx2 v210, v[64:65], s[52:53] offset:288
	s_waitcnt vmcnt(27)
	v_pk_fma_f32 v[60:61], v[60:61], v[128:129], v[116:117]
	v_pk_fma_f32 v[62:63], v[62:63], v[130:131], v[118:119]
	v_add_u32_e32 v210, 0x40000, v207
	v_cvt_pk_bf16_f32 v60, v60, v61
	v_cvt_pk_bf16_f32 v61, v62, v63
	global_store_dwordx2 v210, v[60:61], s[52:53] offset:0
	s_waitcnt vmcnt(26)
	v_pk_fma_f32 v[56:57], v[56:57], v[132:133], v[180:181]
	v_pk_fma_f32 v[58:59], v[58:59], v[134:135], v[182:183]
	v_cvt_pk_bf16_f32 v56, v56, v57
	v_cvt_pk_bf16_f32 v57, v58, v59
	global_store_dwordx2 v210, v[56:57], s[52:53] offset:32
	s_waitcnt vmcnt(26)
	v_pk_fma_f32 v[52:53], v[52:53], v[136:137], v[112:113]
	v_pk_fma_f32 v[54:55], v[54:55], v[138:139], v[114:115]
	v_cvt_pk_bf16_f32 v52, v52, v53
	v_cvt_pk_bf16_f32 v53, v54, v55
	global_store_dwordx2 v210, v[52:53], s[52:53] offset:256
	s_waitcnt vmcnt(25)
	v_pk_fma_f32 v[48:49], v[48:49], v[140:141], v[184:185]
	v_pk_fma_f32 v[50:51], v[50:51], v[142:143], v[186:187]
	v_cvt_pk_bf16_f32 v48, v48, v49
	v_cvt_pk_bf16_f32 v49, v50, v51
	global_store_dwordx2 v210, v[48:49], s[52:53] offset:288
	s_waitcnt vmcnt(25)
	v_pk_fma_f32 v[44:45], v[44:45], v[128:129], v[108:109]
	v_pk_fma_f32 v[46:47], v[46:47], v[130:131], v[110:111]
	v_add_u32_e32 v210, 0x48000, v207
	v_cvt_pk_bf16_f32 v44, v44, v45
	v_cvt_pk_bf16_f32 v45, v46, v47
	global_store_dwordx2 v210, v[44:45], s[52:53] offset:0
	s_waitcnt vmcnt(24)
	v_pk_fma_f32 v[40:41], v[40:41], v[132:133], v[190:191]
	v_pk_fma_f32 v[42:43], v[42:43], v[134:135], v[192:193]
	v_cvt_pk_bf16_f32 v40, v40, v41
	v_cvt_pk_bf16_f32 v41, v42, v43
	global_store_dwordx2 v210, v[40:41], s[52:53] offset:32
	s_waitcnt vmcnt(24)
	v_pk_fma_f32 v[36:37], v[36:37], v[136:137], v[104:105]
	v_pk_fma_f32 v[38:39], v[38:39], v[138:139], v[106:107]
	v_cvt_pk_bf16_f32 v36, v36, v37
	v_cvt_pk_bf16_f32 v37, v38, v39
	global_store_dwordx2 v210, v[36:37], s[52:53] offset:256
	s_waitcnt vmcnt(23)
	v_pk_fma_f32 v[32:33], v[32:33], v[140:141], v[194:195]
	v_pk_fma_f32 v[34:35], v[34:35], v[142:143], v[196:197]
	v_cvt_pk_bf16_f32 v32, v32, v33
	v_cvt_pk_bf16_f32 v33, v34, v35
	global_store_dwordx2 v210, v[32:33], s[52:53] offset:288
	s_waitcnt vmcnt(23)
	v_pk_fma_f32 v[28:29], v[28:29], v[128:129], v[100:101]
	v_pk_fma_f32 v[30:31], v[30:31], v[130:131], v[102:103]
	v_add_u32_e32 v210, 0x50000, v207
	v_cvt_pk_bf16_f32 v28, v28, v29
	v_cvt_pk_bf16_f32 v29, v30, v31
	global_store_dwordx2 v210, v[28:29], s[52:53] offset:0
	s_waitcnt vmcnt(22)
	v_pk_fma_f32 v[24:25], v[24:25], v[132:133], v[198:199]
	v_pk_fma_f32 v[26:27], v[26:27], v[134:135], v[200:201]
	v_cvt_pk_bf16_f32 v24, v24, v25
	v_cvt_pk_bf16_f32 v25, v26, v27
	global_store_dwordx2 v210, v[24:25], s[52:53] offset:32
	s_waitcnt vmcnt(22)
	v_pk_fma_f32 v[20:21], v[20:21], v[136:137], v[96:97]
	v_pk_fma_f32 v[22:23], v[22:23], v[138:139], v[98:99]
	v_cvt_pk_bf16_f32 v20, v20, v21
	v_cvt_pk_bf16_f32 v21, v22, v23
	global_store_dwordx2 v210, v[20:21], s[52:53] offset:256
	s_waitcnt vmcnt(21)
	v_pk_fma_f32 v[16:17], v[16:17], v[140:141], v[202:203]
	v_pk_fma_f32 v[18:19], v[18:19], v[142:143], v[204:205]
	v_cvt_pk_bf16_f32 v16, v16, v17
	v_cvt_pk_bf16_f32 v17, v18, v19
	global_store_dwordx2 v210, v[16:17], s[52:53] offset:288
	s_waitcnt vmcnt(21)
	v_pk_fma_f32 v[12:13], v[12:13], v[128:129], v[92:93]
	v_pk_fma_f32 v[14:15], v[14:15], v[130:131], v[94:95]
	v_add_u32_e32 v210, 0x58000, v207
	v_cvt_pk_bf16_f32 v12, v12, v13
	v_cvt_pk_bf16_f32 v13, v14, v15
	global_store_dwordx2 v210, v[12:13], s[52:53] offset:0
	s_waitcnt vmcnt(20)
	v_pk_fma_f32 v[8:9], v[8:9], v[132:133], v[156:157]
	v_pk_fma_f32 v[10:11], v[10:11], v[134:135], v[158:159]
	v_cvt_pk_bf16_f32 v8, v8, v9
	v_cvt_pk_bf16_f32 v9, v10, v11
	global_store_dwordx2 v210, v[8:9], s[52:53] offset:32
	s_waitcnt vmcnt(20)
	v_pk_fma_f32 v[4:5], v[4:5], v[136:137], v[88:89]
	v_pk_fma_f32 v[6:7], v[6:7], v[138:139], v[90:91]
	v_cvt_pk_bf16_f32 v4, v4, v5
	v_cvt_pk_bf16_f32 v5, v6, v7
	global_store_dwordx2 v210, v[4:5], s[52:53] offset:256
	s_waitcnt vmcnt(19)
	v_pk_fma_f32 v[0:1], v[0:1], v[140:141], v[160:161]
	v_pk_fma_f32 v[2:3], v[2:3], v[142:143], v[162:163]
	v_cvt_pk_bf16_f32 v0, v0, v1
	v_cvt_pk_bf16_f32 v1, v2, v3
	global_store_dwordx2 v210, v[0:1], s[52:53] offset:288
	s_and_b64 vcc, exec, s[6:7]
	s_mov_b64 s[6:7], -1
	s_cbranch_vccnz .LBB0_751
	s_andn2_b64 vcc, exec, s[16:17]
	s_cbranch_vccnz .LBB0_750
	s_barrier
	s_branch .LBB0_750

; __device__ __forceinline__ unsigned cvt_pk_bf16(float lo, float hi) { unsigned r; asm volatile("v_cvt_pk_bf16_f32 %0, %1, %2" : "=v"(r) : "v"(lo), "v"(hi)); return r; }
;     __device__ __forceinline__ void operator()(const f32x4 (&acc)[2][2][4][2], const Unit& u, int wr, int wc, int fr, int fq) const {
;         int row0 = u.pm * BM + wr * 64 + fr + row_off; const bool isctx = row0 >= NLAT; const int b = isctx ? 8 : (row0 >> 12);
;         const void* bp = isctx ? base_ctx : base_lat; void* op = isctx ? out_ctx : out_lat; if (isctx) row0 -= NLAT;
;         const int col0 = u.pn * BM + wc * 32 + 4 * fq;
;         f32x4 gv[2][2];
; #pragma unroll
;         for (int bj = 0; bj < 2; ++bj)
; #pragma unroll
;             for (int n = 0; n < 2; ++n) gv[bj][n] = *(const f32x4*)(gate + b * MODS + col0 + bj * HALF + n * 16);
; #pragma unroll
;         for (int ai = 0; ai < 2; ++ai)
; #pragma unroll
;             for (int m = 0; m < 4; ++m) { const size_t off = (size_t)(row0 + ai * HALF + m * 16) * DM + col0;
; #pragma unroll
;                 for (int bj = 0; bj < 2; ++bj)
; #pragma unroll
;                     for (int n = 0; n < 2; ++n) { const size_t o2 = off + bj * HALF + n * 16; f32x4 bs;
;                         if (BB) { const u32x2 r = *(const u32x2*)((const bf16_t*)bp + o2); bs = (f32x4){__uint_as_float(r.x << 16), __uint_as_float(r.x & 0xffff0000u), __uint_as_float(r.y << 16), __uint_as_float(r.y & 0xffff0000u)}; }
;                         else bs = *(const f32x4*)((const float*)bp + o2);
;                         const f32x4 o = bs + gv[bj][n] * acc[ai][bj][m][n];
;                         if (OB) { u32x2 w; w.x = cvt_pk_bf16(o[0], o[1]); w.y = cvt_pk_bf16(o[2], o[3]); *(u32x2*)((bf16_t*)op + o2) = w; }
;                         else *(f32x4*)((float*)op + o2) = o; } }
;     }
.LBB0_983:
	s_waitcnt lgkmcnt(0)
	v_lshl_add_u32 v215, s65, 8, v166
	v_lshl_or_b32 v214, s66, 8, v168
	v_lshlrev_b32_e32 v212, 11, v215
	v_lshlrev_b32_e32 v213, 11, v215
	v_lshl_add_u32 v212, v214, 1, v212
	v_lshl_add_u32 v213, v214, 1, v213
	v_mov_b32_e32 v216, s65
	v_lshrrev_b32_e32 v216, 4, v216
	v_mul_u32_u24_e32 v216, 0x1800, v216
	v_add_lshl_u32 v214, v214, v216, 2
	global_load_dwordx4 v[128:131], v214, s[16:17] offset:0
	global_load_dwordx4 v[132:135], v214, s[16:17] offset:64
	global_load_dwordx4 v[136:139], v214, s[16:17] offset:512
	global_load_dwordx4 v[140:143], v214, s[16:17] offset:576
	v_mov_b32_e32 v215, v212
	global_load_dwordx2 v[162:163], v215, s[14:15] offset:0
	global_load_dwordx2 v[172:173], v215, s[14:15] offset:32
	global_load_dwordx2 v[174:175], v215, s[14:15] offset:256
	global_load_dwordx2 v[176:177], v215, s[14:15] offset:288
	v_add_u32_e32 v215, 0x8000, v212
	global_load_dwordx2 v[178:179], v215, s[14:15] offset:0
	global_load_dwordx2 v[180:181], v215, s[14:15] offset:32
	global_load_dwordx2 v[182:183], v215, s[14:15] offset:256
	global_load_dwordx2 v[184:185], v215, s[14:15] offset:288
	v_add_u32_e32 v215, 0x10000, v212
	global_load_dwordx2 v[186:187], v215, s[14:15] offset:0
	global_load_dwordx2 v[190:191], v215, s[14:15] offset:32
	global_load_dwordx2 v[192:193], v215, s[14:15] offset:256
	global_load_dwordx2 v[194:195], v215, s[14:15] offset:288
	v_add_u32_e32 v215, 0x18000, v212
	global_load_dwordx2 v[196:197], v215, s[14:15] offset:0
	global_load_dwordx2 v[198:199], v215, s[14:15] offset:32
	global_load_dwordx2 v[200:201], v215, s[14:15] offset:256
	global_load_dwordx2 v[202:203], v215, s[14:15] offset:288
	v_add_u32_e32 v215, 0x40000, v212
	global_load_dwordx2 v[204:205], v215, s[14:15] offset:0
	global_load_dwordx2 v[206:207], v215, s[14:15] offset:32
	global_load_dwordx2 v[208:209], v215, s[14:15] offset:256
	global_load_dwordx2 v[210:211], v215, s[14:15] offset:288
	s_waitcnt vmcnt(19)
	v_lshlrev_b32_e32 v160, 16, v162
	v_and_b32_e32 v161, 0xffff0000, v162
	v_lshlrev_b32_e32 v162, 16, v163
	v_and_b32_e32 v163, 0xffff0000, v163
	v_pk_fma_f32 v[124:125], v[124:125], v[128:129], v[160:161]
	v_pk_fma_f32 v[126:127], v[126:127], v[130:131], v[162:163]
	v_mov_b32_e32 v216, v213
	v_cvt_pk_bf16_f32 v124, v124, v125
	v_cvt_pk_bf16_f32 v125, v126, v127
	global_store_dwordx2 v216, v[124:125], s[14:15] offset:0
	v_add_u32_e32 v215, 0x48000, v212
	global_load_dwordx2 v[162:163], v215, s[14:15] offset:0
	s_waitcnt vmcnt(20)
	v_lshlrev_b32_e32 v160, 16, v172
	v_and_b32_e32 v161, 0xffff0000, v172
	v_lshlrev_b32_e32 v172, 16, v173
	v_and_b32_e32 v173, 0xffff0000, v173
	v_pk_fma_f32 v[120:121], v[120:121], v[132:133], v[160:161]
	v_pk_fma_f32 v[122:123], v[122:123], v[134:135], v[172:173]
	v_cvt_pk_bf16_f32 v120, v120, v121
	v_cvt_pk_bf16_f32 v121, v122, v123
	global_store_dwordx2 v216, v[120:121], s[14:15] offset:32
	global_load_dwordx2 v[172:173], v215, s[14:15] offset:32
	global_load_dwordx2 v[124:125], v215, s[14:15] offset:256
	global_load_dwordx2 v[126:127], v215, s[14:15] offset:288
	s_waitcnt vmcnt(23)
	v_lshlrev_b32_e32 v160, 16, v174
	v_and_b32_e32 v161, 0xffff0000, v174
	v_lshlrev_b32_e32 v174, 16, v175
	v_and_b32_e32 v175, 0xffff0000, v175
	v_pk_fma_f32 v[116:117], v[116:117], v[136:137], v[160:161]
	v_pk_fma_f32 v[118:119], v[118:119], v[138:139], v[174:175]
	v_cvt_pk_bf16_f32 v116, v116, v117
	v_cvt_pk_bf16_f32 v117, v118, v119
	global_store_dwordx2 v216, v[116:117], s[14:15] offset:256
	v_add_u32_e32 v215, 0x50000, v212
	global_load_dwordx2 v[174:175], v215, s[14:15] offset:0
	global_load_dwordx2 v[120:121], v215, s[14:15] offset:32
	global_load_dwordx2 v[122:123], v215, s[14:15] offset:256
	s_waitcnt vmcnt(26)
	v_lshlrev_b32_e32 v160, 16, v176
	v_and_b32_e32 v161, 0xffff0000, v176
	v_lshlrev_b32_e32 v176, 16, v177
	v_and_b32_e32 v177, 0xffff0000, v177
	v_pk_fma_f32 v[112:113], v[112:113], v[140:141], v[160:161]
	v_pk_fma_f32 v[114:115], v[114:115], v[142:143], v[176:177]
	v_cvt_pk_bf16_f32 v112, v112, v113
	v_cvt_pk_bf16_f32 v113, v114, v115
	global_store_dwordx2 v216, v[112:113], s[14:15] offset:288
	global_load_dwordx2 v[176:177], v215, s[14:15] offset:288
	v_add_u32_e32 v215, 0x58000, v212
	global_load_dwordx2 v[116:117], v215, s[14:15] offset:0
	global_load_dwordx2 v[118:119], v215, s[14:15] offset:32
	s_waitcnt vmcnt(29)
	v_lshlrev_b32_e32 v160, 16, v178
	v_and_b32_e32 v161, 0xffff0000, v178
	v_lshlrev_b32_e32 v178, 16, v179
	v_and_b32_e32 v179, 0xffff0000, v179
	v_pk_fma_f32 v[108:109], v[108:109], v[128:129], v[160:161]
	v_pk_fma_f32 v[110:111], v[110:111], v[130:131], v[178:179]
	v_add_u32_e32 v216, 0x8000, v213
	v_cvt_pk_bf16_f32 v108, v108, v109
	v_cvt_pk_bf16_f32 v109, v110, v111
	global_store_dwordx2 v216, v[108:109], s[14:15] offset:0
	global_load_dwordx2 v[178:179], v215, s[14:15] offset:256
	global_load_dwordx2 v[112:113], v215, s[14:15] offset:288
	s_waitcnt vmcnt(31)
	v_lshlrev_b32_e32 v160, 16, v180
	v_and_b32_e32 v161, 0xffff0000, v180
	v_lshlrev_b32_e32 v180, 16, v181
	v_and_b32_e32 v181, 0xffff0000, v181
	v_pk_fma_f32 v[104:105], v[104:105], v[132:133], v[160:161]
	v_pk_fma_f32 v[106:107], v[106:107], v[134:135], v[180:181]
	v_cvt_pk_bf16_f32 v104, v104, v105
	v_cvt_pk_bf16_f32 v105, v106, v107
	global_store_dwordx2 v216, v[104:105], s[14:15] offset:32
	s_waitcnt vmcnt(31)
	v_lshlrev_b32_e32 v160, 16, v182
	v_and_b32_e32 v161, 0xffff0000, v182
	v_lshlrev_b32_e32 v182, 16, v183
	v_and_b32_e32 v183, 0xffff0000, v183
	v_pk_fma_f32 v[100:101], v[100:101], v[136:137], v[160:161]
	v_pk_fma_f32 v[102:103], v[102:103], v[138:139], v[182:183]
	v_cvt_pk_bf16_f32 v100, v100, v101
	v_cvt_pk_bf16_f32 v101, v102, v103
	global_store_dwordx2 v216, v[100:101], s[14:15] offset:256
	s_waitcnt vmcnt(31)
; __device__ __forceinline__ unsigned cvt_pk_bf16(float lo, float hi) { unsigned r; asm volatile("v_cvt_pk_bf16_f32 %0, %1, %2" : "=v"(r) : "v"(lo), "v"(hi)); return r; }
;     __device__ __forceinline__ void operator()(const f32x4 (&acc)[2][2][4][2], const Unit& u, int wr, int wc, int fr, int fq) const {
;         int row0 = u.pm * BM + wr * 64 + fr + row_off; const bool isctx = row0 >= NLAT; const int b = isctx ? 8 : (row0 >> 12);
;         const void* bp = isctx ? base_ctx : base_lat; void* op = isctx ? out_ctx : out_lat; if (isctx) row0 -= NLAT;
;         const int col0 = u.pn * BM + wc * 32 + 4 * fq;
;         f32x4 gv[2][2];
; #pragma unroll
;         for (int bj = 0; bj < 2; ++bj)
; #pragma unroll
;             for (int n = 0; n < 2; ++n) gv[bj][n] = *(const f32x4*)(gate + b * MODS + col0 + bj * HALF + n * 16);
; #pragma unroll
;         for (int ai = 0; ai < 2; ++ai)
; #pragma unroll
;             for (int m = 0; m < 4; ++m) { const size_t off = (size_t)(row0 + ai * HALF + m * 16) * DM + col0;
; #pragma unroll
;                 for (int bj = 0; bj < 2; ++bj)
; #pragma unroll
;                     for (int n = 0; n < 2; ++n) { const size_t o2 = off + bj * HALF + n * 16; f32x4 bs;
;                         if (BB) { const u32x2 r = *(const u32x2*)((const bf16_t*)bp + o2); bs = (f32x4){__uint_as_float(r.x << 16), __uint_as_float(r.x & 0xffff0000u), __uint_as_float(r.y << 16), __uint_as_float(r.y & 0xffff0000u)}; }
;                         else bs = *(const f32x4*)((const float*)bp + o2);
;                         const f32x4 o = bs + gv[bj][n] * acc[ai][bj][m][n];
;                         if (OB) { u32x2 w; w.x = cvt_pk_bf16(o[0], o[1]); w.y = cvt_pk_bf16(o[2], o[3]); *(u32x2*)((bf16_t*)op + o2) = w; }
;                         else *(f32x4*)((float*)op + o2) = o; } }
;     }
	v_lshlrev_b32_e32 v160, 16, v184
	v_and_b32_e32 v161, 0xffff0000, v184
	v_lshlrev_b32_e32 v184, 16, v185
	v_and_b32_e32 v185, 0xffff0000, v185
	v_pk_fma_f32 v[96:97], v[96:97], v[140:141], v[160:161]
	v_pk_fma_f32 v[98:99], v[98:99], v[142:143], v[184:185]
	v_cvt_pk_bf16_f32 v96, v96, v97
	v_cvt_pk_bf16_f32 v97, v98, v99
	global_store_dwordx2 v216, v[96:97], s[14:15] offset:288
	s_waitcnt vmcnt(31)
	v_lshlrev_b32_e32 v160, 16, v186
	v_and_b32_e32 v161, 0xffff0000, v186
	v_lshlrev_b32_e32 v186, 16, v187
	v_and_b32_e32 v187, 0xffff0000, v187
	v_pk_fma_f32 v[92:93], v[92:93], v[128:129], v[160:161]
	v_pk_fma_f32 v[94:95], v[94:95], v[130:131], v[186:187]
	v_add_u32_e32 v216, 0x10000, v213
	v_cvt_pk_bf16_f32 v92, v92, v93
	v_cvt_pk_bf16_f32 v93, v94, v95
	global_store_dwordx2 v216, v[92:93], s[14:15] offset:0
	s_waitcnt vmcnt(31)
	v_lshlrev_b32_e32 v160, 16, v190
	v_and_b32_e32 v161, 0xffff0000, v190
	v_lshlrev_b32_e32 v190, 16, v191
	v_and_b32_e32 v191, 0xffff0000, v191
	v_pk_fma_f32 v[88:89], v[88:89], v[132:133], v[160:161]
	v_pk_fma_f32 v[90:91], v[90:91], v[134:135], v[190:191]
	v_cvt_pk_bf16_f32 v88, v88, v89
	v_cvt_pk_bf16_f32 v89, v90, v91
	global_store_dwordx2 v216, v[88:89], s[14:15] offset:32
	s_waitcnt vmcnt(31)
	v_lshlrev_b32_e32 v160, 16, v192
	v_and_b32_e32 v161, 0xffff0000, v192
	v_lshlrev_b32_e32 v192, 16, v193
	v_and_b32_e32 v193, 0xffff0000, v193
	v_pk_fma_f32 v[84:85], v[84:85], v[136:137], v[160:161]
	v_pk_fma_f32 v[86:87], v[86:87], v[138:139], v[192:193]
	v_cvt_pk_bf16_f32 v84, v84, v85
	v_cvt_pk_bf16_f32 v85, v86, v87
	global_store_dwordx2 v216, v[84:85], s[14:15] offset:256
	s_waitcnt vmcnt(31)
	v_lshlrev_b32_e32 v160, 16, v194
	v_and_b32_e32 v161, 0xffff0000, v194
	v_lshlrev_b32_e32 v194, 16, v195
	v_and_b32_e32 v195, 0xffff0000, v195
	v_pk_fma_f32 v[80:81], v[80:81], v[140:141], v[160:161]
	v_pk_fma_f32 v[82:83], v[82:83], v[142:143], v[194:195]
	v_cvt_pk_bf16_f32 v80, v80, v81
	v_cvt_pk_bf16_f32 v81, v82, v83
	global_store_dwordx2 v216, v[80:81], s[14:15] offset:288
	s_waitcnt vmcnt(31)
	v_lshlrev_b32_e32 v160, 16, v196
	v_and_b32_e32 v161, 0xffff0000, v196
	v_lshlrev_b32_e32 v196, 16, v197
	v_and_b32_e32 v197, 0xffff0000, v197
	v_pk_fma_f32 v[76:77], v[76:77], v[128:129], v[160:161]
	v_pk_fma_f32 v[78:79], v[78:79], v[130:131], v[196:197]
	v_add_u32_e32 v216, 0x18000, v213
	v_cvt_pk_bf16_f32 v76, v76, v77
	v_cvt_pk_bf16_f32 v77, v78, v79
	global_store_dwordx2 v216, v[76:77], s[14:15] offset:0
	s_waitcnt vmcnt(31)
	v_lshlrev_b32_e32 v160, 16, v198
	v_and_b32_e32 v161, 0xffff0000, v198
	v_lshlrev_b32_e32 v198, 16, v199
	v_and_b32_e32 v199, 0xffff0000, v199
	v_pk_fma_f32 v[72:73], v[72:73], v[132:133], v[160:161]
	v_pk_fma_f32 v[74:75], v[74:75], v[134:135], v[198:199]
	v_cvt_pk_bf16_f32 v72, v72, v73
	v_cvt_pk_bf16_f32 v73, v74, v75
	global_store_dwordx2 v216, v[72:73], s[14:15] offset:32
	s_waitcnt vmcnt(31)
	v_lshlrev_b32_e32 v160, 16, v200
	v_and_b32_e32 v161, 0xffff0000, v200
	v_lshlrev_b32_e32 v200, 16, v201
	v_and_b32_e32 v201, 0xffff0000, v201
	v_pk_fma_f32 v[68:69], v[68:69], v[136:137], v[160:161]
	v_pk_fma_f32 v[70:71], v[70:71], v[138:139], v[200:201]
	v_cvt_pk_bf16_f32 v68, v68, v69
	v_cvt_pk_bf16_f32 v69, v70, v71
	global_store_dwordx2 v216, v[68:69], s[14:15] offset:256
	s_waitcnt vmcnt(31)
	v_lshlrev_b32_e32 v160, 16, v202
	v_and_b32_e32 v161, 0xffff0000, v202
	v_lshlrev_b32_e32 v202, 16, v203
	v_and_b32_e32 v203, 0xffff0000, v203
	v_pk_fma_f32 v[64:65], v[64:65], v[140:141], v[160:161]
	v_pk_fma_f32 v[66:67], v[66:67], v[142:143], v[202:203]
	v_cvt_pk_bf16_f32 v64, v64, v65
	v_cvt_pk_bf16_f32 v65, v66, v67
	global_store_dwordx2 v216, v[64:65], s[14:15] offset:288
	s_waitcnt vmcnt(31)
	v_lshlrev_b32_e32 v160, 16, v204
	v_and_b32_e32 v161, 0xffff0000, v204
	v_lshlrev_b32_e32 v204, 16, v205
	v_and_b32_e32 v205, 0xffff0000, v205
	v_pk_fma_f32 v[60:61], v[60:61], v[128:129], v[160:161]
	v_pk_fma_f32 v[62:63], v[62:63], v[130:131], v[204:205]
	v_add_u32_e32 v216, 0x40000, v213
	v_cvt_pk_bf16_f32 v60, v60, v61
	v_cvt_pk_bf16_f32 v61, v62, v63
	global_store_dwordx2 v216, v[60:61], s[14:15] offset:0
	s_waitcnt vmcnt(31)
	v_lshlrev_b32_e32 v160, 16, v206
	v_and_b32_e32 v161, 0xffff0000, v206
	v_lshlrev_b32_e32 v206, 16, v207
	v_and_b32_e32 v207, 0xffff0000, v207
	v_pk_fma_f32 v[56:57], v[56:57], v[132:133], v[160:161]
	v_pk_fma_f32 v[58:59], v[58:59], v[134:135], v[206:207]
	v_cvt_pk_bf16_f32 v56, v56, v57
	v_cvt_pk_bf16_f32 v57, v58, v59
	global_store_dwordx2 v216, v[56:57], s[14:15] offset:32
	s_waitcnt vmcnt(31)
	v_lshlrev_b32_e32 v160, 16, v208
	v_and_b32_e32 v161, 0xffff0000, v208
	v_lshlrev_b32_e32 v208, 16, v209
	v_and_b32_e32 v209, 0xffff0000, v209
	v_pk_fma_f32 v[52:53], v[52:53], v[136:137], v[160:161]
	v_pk_fma_f32 v[54:55], v[54:55], v[138:139], v[208:209]
	v_cvt_pk_bf16_f32 v52, v52, v53
	v_cvt_pk_bf16_f32 v53, v54, v55
	global_store_dwordx2 v216, v[52:53], s[14:15] offset:256
	s_waitcnt vmcnt(31)
	v_lshlrev_b32_e32 v160, 16, v210
	v_and_b32_e32 v161, 0xffff0000, v210
	v_lshlrev_b32_e32 v210, 16, v211
	v_and_b32_e32 v211, 0xffff0000, v211
	v_pk_fma_f32 v[48:49], v[48:49], v[140:141], v[160:161]
	v_pk_fma_f32 v[50:51], v[50:51], v[142:143], v[210:211]
	v_cvt_pk_bf16_f32 v48, v48, v49
	v_cvt_pk_bf16_f32 v49, v50, v51
	global_store_dwordx2 v216, v[48:49], s[14:15] offset:288
	s_waitcnt vmcnt(30)
; __device__ __forceinline__ unsigned cvt_pk_bf16(float lo, float hi) { unsigned r; asm volatile("v_cvt_pk_bf16_f32 %0, %1, %2" : "=v"(r) : "v"(lo), "v"(hi)); return r; }
;     __device__ __forceinline__ void operator()(const f32x4 (&acc)[2][2][4][2], const Unit& u, int wr, int wc, int fr, int fq) const {
;         int row0 = u.pm * BM + wr * 64 + fr + row_off; const bool isctx = row0 >= NLAT; const int b = isctx ? 8 : (row0 >> 12);
;         const void* bp = isctx ? base_ctx : base_lat; void* op = isctx ? out_ctx : out_lat; if (isctx) row0 -= NLAT;
;         const int col0 = u.pn * BM + wc * 32 + 4 * fq;
;         f32x4 gv[2][2];
; #pragma unroll
;         for (int bj = 0; bj < 2; ++bj)
; #pragma unroll
;             for (int n = 0; n < 2; ++n) gv[bj][n] = *(const f32x4*)(gate + b * MODS + col0 + bj * HALF + n * 16);
; #pragma unroll
;         for (int ai = 0; ai < 2; ++ai)
; #pragma unroll
;             for (int m = 0; m < 4; ++m) { const size_t off = (size_t)(row0 + ai * HALF + m * 16) * DM + col0;
; #pragma unroll
;                 for (int bj = 0; bj < 2; ++bj)
; #pragma unroll
;                     for (int n = 0; n < 2; ++n) { const size_t o2 = off + bj * HALF + n * 16; f32x4 bs;
;                         if (BB) { const u32x2 r = *(const u32x2*)((const bf16_t*)bp + o2); bs = (f32x4){__uint_as_float(r.x << 16), __uint_as_float(r.x & 0xffff0000u), __uint_as_float(r.y << 16), __uint_as_float(r.y & 0xffff0000u)}; }
;                         else bs = *(const f32x4*)((const float*)bp + o2);
;                         const f32x4 o = bs + gv[bj][n] * acc[ai][bj][m][n];
;                         if (OB) { u32x2 w; w.x = cvt_pk_bf16(o[0], o[1]); w.y = cvt_pk_bf16(o[2], o[3]); *(u32x2*)((bf16_t*)op + o2) = w; }
;                         else *(f32x4*)((float*)op + o2) = o; } }
;     }
	v_lshlrev_b32_e32 v160, 16, v162
	v_and_b32_e32 v161, 0xffff0000, v162
	v_lshlrev_b32_e32 v162, 16, v163
	v_and_b32_e32 v163, 0xffff0000, v163
	v_pk_fma_f32 v[44:45], v[44:45], v[128:129], v[160:161]
	v_pk_fma_f32 v[46:47], v[46:47], v[130:131], v[162:163]
	v_add_u32_e32 v216, 0x48000, v213
	v_cvt_pk_bf16_f32 v44, v44, v45
	v_cvt_pk_bf16_f32 v45, v46, v47
	global_store_dwordx2 v216, v[44:45], s[14:15] offset:0
	s_waitcnt vmcnt(29)
	v_lshlrev_b32_e32 v160, 16, v172
	v_and_b32_e32 v161, 0xffff0000, v172
	v_lshlrev_b32_e32 v172, 16, v173
	v_and_b32_e32 v173, 0xffff0000, v173
	v_pk_fma_f32 v[40:41], v[40:41], v[132:133], v[160:161]
	v_pk_fma_f32 v[42:43], v[42:43], v[134:135], v[172:173]
	v_cvt_pk_bf16_f32 v40, v40, v41
	v_cvt_pk_bf16_f32 v41, v42, v43
	global_store_dwordx2 v216, v[40:41], s[14:15] offset:32
	s_waitcnt vmcnt(29)
	v_lshlrev_b32_e32 v160, 16, v124
	v_and_b32_e32 v161, 0xffff0000, v124
	v_lshlrev_b32_e32 v124, 16, v125
	v_and_b32_e32 v125, 0xffff0000, v125
	v_pk_fma_f32 v[36:37], v[36:37], v[136:137], v[160:161]
	v_pk_fma_f32 v[38:39], v[38:39], v[138:139], v[124:125]
	v_cvt_pk_bf16_f32 v36, v36, v37
	v_cvt_pk_bf16_f32 v37, v38, v39
	global_store_dwordx2 v216, v[36:37], s[14:15] offset:256
	s_waitcnt vmcnt(29)
	v_lshlrev_b32_e32 v160, 16, v126
	v_and_b32_e32 v161, 0xffff0000, v126
	v_lshlrev_b32_e32 v126, 16, v127
	v_and_b32_e32 v127, 0xffff0000, v127
	v_pk_fma_f32 v[32:33], v[32:33], v[140:141], v[160:161]
	v_pk_fma_f32 v[34:35], v[34:35], v[142:143], v[126:127]
	v_cvt_pk_bf16_f32 v32, v32, v33
	v_cvt_pk_bf16_f32 v33, v34, v35
	global_store_dwordx2 v216, v[32:33], s[14:15] offset:288
	s_waitcnt vmcnt(28)
	v_lshlrev_b32_e32 v160, 16, v174
	v_and_b32_e32 v161, 0xffff0000, v174
	v_lshlrev_b32_e32 v174, 16, v175
	v_and_b32_e32 v175, 0xffff0000, v175
	v_pk_fma_f32 v[28:29], v[28:29], v[128:129], v[160:161]
	v_pk_fma_f32 v[30:31], v[30:31], v[130:131], v[174:175]
	v_add_u32_e32 v216, 0x50000, v213
	v_cvt_pk_bf16_f32 v28, v28, v29
	v_cvt_pk_bf16_f32 v29, v30, v31
	global_store_dwordx2 v216, v[28:29], s[14:15] offset:0
	s_waitcnt vmcnt(28)
	v_lshlrev_b32_e32 v160, 16, v120
	v_and_b32_e32 v161, 0xffff0000, v120
	v_lshlrev_b32_e32 v120, 16, v121
	v_and_b32_e32 v121, 0xffff0000, v121
	v_pk_fma_f32 v[24:25], v[24:25], v[132:133], v[160:161]
	v_pk_fma_f32 v[26:27], v[26:27], v[134:135], v[120:121]
	v_cvt_pk_bf16_f32 v24, v24, v25
	v_cvt_pk_bf16_f32 v25, v26, v27
	global_store_dwordx2 v216, v[24:25], s[14:15] offset:32
	s_waitcnt vmcnt(28)
	v_lshlrev_b32_e32 v160, 16, v122
	v_and_b32_e32 v161, 0xffff0000, v122
	v_lshlrev_b32_e32 v122, 16, v123
	v_and_b32_e32 v123, 0xffff0000, v123
	v_pk_fma_f32 v[20:21], v[20:21], v[136:137], v[160:161]
	v_pk_fma_f32 v[22:23], v[22:23], v[138:139], v[122:123]
	v_cvt_pk_bf16_f32 v20, v20, v21
	v_cvt_pk_bf16_f32 v21, v22, v23
	global_store_dwordx2 v216, v[20:21], s[14:15] offset:256
	s_waitcnt vmcnt(27)
	v_lshlrev_b32_e32 v160, 16, v176
	v_and_b32_e32 v161, 0xffff0000, v176
	v_lshlrev_b32_e32 v176, 16, v177
	v_and_b32_e32 v177, 0xffff0000, v177
	v_pk_fma_f32 v[16:17], v[16:17], v[140:141], v[160:161]
	v_pk_fma_f32 v[18:19], v[18:19], v[142:143], v[176:177]
	v_cvt_pk_bf16_f32 v16, v16, v17
	v_cvt_pk_bf16_f32 v17, v18, v19
	global_store_dwordx2 v216, v[16:17], s[14:15] offset:288
	s_waitcnt vmcnt(27)
	v_lshlrev_b32_e32 v160, 16, v116
	v_and_b32_e32 v161, 0xffff0000, v116
	v_lshlrev_b32_e32 v116, 16, v117
	v_and_b32_e32 v117, 0xffff0000, v117
	v_pk_fma_f32 v[12:13], v[12:13], v[128:129], v[160:161]
	v_pk_fma_f32 v[14:15], v[14:15], v[130:131], v[116:117]
	v_add_u32_e32 v216, 0x58000, v213
	v_cvt_pk_bf16_f32 v12, v12, v13
	v_cvt_pk_bf16_f32 v13, v14, v15
	global_store_dwordx2 v216, v[12:13], s[14:15] offset:0
	s_waitcnt vmcnt(27)
	v_lshlrev_b32_e32 v160, 16, v118
	v_and_b32_e32 v161, 0xffff0000, v118
	v_lshlrev_b32_e32 v118, 16, v119
	v_and_b32_e32 v119, 0xffff0000, v119
	v_pk_fma_f32 v[8:9], v[8:9], v[132:133], v[160:161]
	v_pk_fma_f32 v[10:11], v[10:11], v[134:135], v[118:119]
	v_cvt_pk_bf16_f32 v8, v8, v9
	v_cvt_pk_bf16_f32 v9, v10, v11
	global_store_dwordx2 v216, v[8:9], s[14:15] offset:32
	s_waitcnt vmcnt(26)
	v_lshlrev_b32_e32 v160, 16, v178
	v_and_b32_e32 v161, 0xffff0000, v178
	v_lshlrev_b32_e32 v178, 16, v179
	v_and_b32_e32 v179, 0xffff0000, v179
	v_pk_fma_f32 v[4:5], v[4:5], v[136:137], v[160:161]
	v_pk_fma_f32 v[6:7], v[6:7], v[138:139], v[178:179]
	v_cvt_pk_bf16_f32 v4, v4, v5
	v_cvt_pk_bf16_f32 v5, v6, v7
	global_store_dwordx2 v216, v[4:5], s[14:15] offset:256
	s_waitcnt vmcnt(26)
	v_lshlrev_b32_e32 v160, 16, v112
	v_and_b32_e32 v161, 0xffff0000, v112
	v_lshlrev_b32_e32 v112, 16, v113
	v_and_b32_e32 v113, 0xffff0000, v113
	v_pk_fma_f32 v[0:1], v[0:1], v[140:141], v[160:161]
	v_pk_fma_f32 v[2:3], v[2:3], v[142:143], v[112:113]
	v_cvt_pk_bf16_f32 v0, v0, v1
	v_cvt_pk_bf16_f32 v1, v2, v3
	global_store_dwordx2 v216, v[0:1], s[14:15] offset:288
	s_and_b64 vcc, exec, s[6:7]
	s_mov_b64 s[6:7], -1
	s_cbranch_vccnz .LBB0_967
	s_andn2_b64 vcc, exec, s[12:13]
	s_cbranch_vccnz .LBB0_966
	s_barrier
	s_branch .LBB0_966

; __device__ __forceinline__ unsigned cvt_pk_bf16(float lo, float hi) { unsigned r; asm volatile("v_cvt_pk_bf16_f32 %0, %1, %2" : "=v"(r) : "v"(lo), "v"(hi)); return r; }
;     __device__ __forceinline__ void operator()(const f32x4 (&acc)[2][2][4][2], const Unit& u, int wr, int wc, int fr, int fq) const {
;         int row0 = u.pm * BM + wr * 64 + fr + row_off; const bool isctx = row0 >= NLAT; const int b = isctx ? 8 : (row0 >> 12);
;         const void* bp = isctx ? base_ctx : base_lat; void* op = isctx ? out_ctx : out_lat; if (isctx) row0 -= NLAT;
;         const int col0 = u.pn * BM + wc * 32 + 4 * fq;
;         f32x4 gv[2][2];
; #pragma unroll
;         for (int bj = 0; bj < 2; ++bj)
; #pragma unroll
;             for (int n = 0; n < 2; ++n) gv[bj][n] = *(const f32x4*)(gate + b * MODS + col0 + bj * HALF + n * 16);
; #pragma unroll
;         for (int ai = 0; ai < 2; ++ai)
; #pragma unroll
;             for (int m = 0; m < 4; ++m) { const size_t off = (size_t)(row0 + ai * HALF + m * 16) * DM + col0;
; #pragma unroll
;                 for (int bj = 0; bj < 2; ++bj)
; #pragma unroll
;                     for (int n = 0; n < 2; ++n) { const size_t o2 = off + bj * HALF + n * 16; f32x4 bs;
;                         if (BB) { const u32x2 r = *(const u32x2*)((const bf16_t*)bp + o2); bs = (f32x4){__uint_as_float(r.x << 16), __uint_as_float(r.x & 0xffff0000u), __uint_as_float(r.y << 16), __uint_as_float(r.y & 0xffff0000u)}; }
;                         else bs = *(const f32x4*)((const float*)bp + o2);
;                         const f32x4 o = bs + gv[bj][n] * acc[ai][bj][m][n];
;                         if (OB) { u32x2 w; w.x = cvt_pk_bf16(o[0], o[1]); w.y = cvt_pk_bf16(o[2], o[3]); *(u32x2*)((bf16_t*)op + o2) = w; }
;                         else *(f32x4*)((float*)op + o2) = o; } }
;     }
.LBB0_1682:
	s_waitcnt lgkmcnt(0)
	v_lshl_add_u32 v215, s66, 8, v166
	v_lshl_or_b32 v214, s88, 8, v168
	v_lshlrev_b32_e32 v212, 11, v215
	v_lshlrev_b32_e32 v213, 11, v215
	v_lshl_add_u32 v212, v214, 1, v212
	v_lshl_add_u32 v213, v214, 1, v213
	v_mov_b32_e32 v216, s66
	v_lshrrev_b32_e32 v216, 4, v216
	v_mul_u32_u24_e32 v216, 0x1800, v216
	v_add_lshl_u32 v214, v214, v216, 2
	global_load_dwordx4 v[120:123], v214, s[20:21] offset:0
	global_load_dwordx4 v[128:131], v214, s[20:21] offset:64
	global_load_dwordx4 v[136:139], v214, s[20:21] offset:512
	global_load_dwordx4 v[140:143], v214, s[20:21] offset:576
	v_mov_b32_e32 v215, v212
	global_load_dwordx2 v[162:163], v215, s[16:17] offset:0
	global_load_dwordx2 v[172:173], v215, s[16:17] offset:32
	global_load_dwordx2 v[174:175], v215, s[16:17] offset:256
	global_load_dwordx2 v[176:177], v215, s[16:17] offset:288
	v_add_u32_e32 v215, 0x8000, v212
	global_load_dwordx2 v[178:179], v215, s[16:17] offset:0
	global_load_dwordx2 v[180:181], v215, s[16:17] offset:32
	global_load_dwordx2 v[182:183], v215, s[16:17] offset:256
	global_load_dwordx2 v[184:185], v215, s[16:17] offset:288
	v_add_u32_e32 v215, 0x10000, v212
	global_load_dwordx2 v[186:187], v215, s[16:17] offset:0
	global_load_dwordx2 v[190:191], v215, s[16:17] offset:32
	global_load_dwordx2 v[192:193], v215, s[16:17] offset:256
	global_load_dwordx2 v[194:195], v215, s[16:17] offset:288
	v_add_u32_e32 v215, 0x18000, v212
	global_load_dwordx2 v[196:197], v215, s[16:17] offset:0
	global_load_dwordx2 v[198:199], v215, s[16:17] offset:32
	global_load_dwordx2 v[200:201], v215, s[16:17] offset:256
	global_load_dwordx2 v[202:203], v215, s[16:17] offset:288
	v_add_u32_e32 v215, 0x40000, v212
	global_load_dwordx2 v[204:205], v215, s[16:17] offset:0
	global_load_dwordx2 v[206:207], v215, s[16:17] offset:32
	global_load_dwordx2 v[208:209], v215, s[16:17] offset:256
	global_load_dwordx2 v[210:211], v215, s[16:17] offset:288
	s_waitcnt vmcnt(19)
	v_lshlrev_b32_e32 v160, 16, v162
	v_and_b32_e32 v161, 0xffff0000, v162
	v_lshlrev_b32_e32 v162, 16, v163
	v_and_b32_e32 v163, 0xffff0000, v163
	v_pk_fma_f32 v[132:133], v[132:133], v[120:121], v[160:161]
	v_pk_fma_f32 v[134:135], v[134:135], v[122:123], v[162:163]
	v_mov_b32_e32 v216, v213
	v_cvt_pk_bf16_f32 v132, v132, v133
	v_cvt_pk_bf16_f32 v133, v134, v135
	global_store_dwordx2 v216, v[132:133], s[18:19] offset:0
	v_add_u32_e32 v215, 0x48000, v212
	global_load_dwordx2 v[162:163], v215, s[16:17] offset:0
	s_waitcnt vmcnt(20)
	v_lshlrev_b32_e32 v160, 16, v172
	v_and_b32_e32 v161, 0xffff0000, v172
	v_lshlrev_b32_e32 v172, 16, v173
	v_and_b32_e32 v173, 0xffff0000, v173
	v_pk_fma_f32 v[124:125], v[124:125], v[128:129], v[160:161]
	v_pk_fma_f32 v[126:127], v[126:127], v[130:131], v[172:173]
	v_cvt_pk_bf16_f32 v124, v124, v125
	v_cvt_pk_bf16_f32 v125, v126, v127
	global_store_dwordx2 v216, v[124:125], s[18:19] offset:32
	global_load_dwordx2 v[172:173], v215, s[16:17] offset:32
	global_load_dwordx2 v[132:133], v215, s[16:17] offset:256
	global_load_dwordx2 v[134:135], v215, s[16:17] offset:288
	s_waitcnt vmcnt(23)
	v_lshlrev_b32_e32 v160, 16, v174
	v_and_b32_e32 v161, 0xffff0000, v174
	v_lshlrev_b32_e32 v174, 16, v175
	v_and_b32_e32 v175, 0xffff0000, v175
	v_pk_fma_f32 v[116:117], v[116:117], v[136:137], v[160:161]
	v_pk_fma_f32 v[118:119], v[118:119], v[138:139], v[174:175]
	v_cvt_pk_bf16_f32 v116, v116, v117
	v_cvt_pk_bf16_f32 v117, v118, v119
	global_store_dwordx2 v216, v[116:117], s[18:19] offset:256
	v_add_u32_e32 v215, 0x50000, v212
	global_load_dwordx2 v[174:175], v215, s[16:17] offset:0
	global_load_dwordx2 v[124:125], v215, s[16:17] offset:32
	global_load_dwordx2 v[126:127], v215, s[16:17] offset:256
	s_waitcnt vmcnt(26)
	v_lshlrev_b32_e32 v160, 16, v176
	v_and_b32_e32 v161, 0xffff0000, v176
	v_lshlrev_b32_e32 v176, 16, v177
	v_and_b32_e32 v177, 0xffff0000, v177
	v_pk_fma_f32 v[112:113], v[112:113], v[140:141], v[160:161]
	v_pk_fma_f32 v[114:115], v[114:115], v[142:143], v[176:177]
	v_cvt_pk_bf16_f32 v112, v112, v113
	v_cvt_pk_bf16_f32 v113, v114, v115
	global_store_dwordx2 v216, v[112:113], s[18:19] offset:288
	global_load_dwordx2 v[176:177], v215, s[16:17] offset:288
	v_add_u32_e32 v215, 0x58000, v212
	global_load_dwordx2 v[116:117], v215, s[16:17] offset:0
	global_load_dwordx2 v[118:119], v215, s[16:17] offset:32
	s_waitcnt vmcnt(29)
	v_lshlrev_b32_e32 v160, 16, v178
	v_and_b32_e32 v161, 0xffff0000, v178
	v_lshlrev_b32_e32 v178, 16, v179
	v_and_b32_e32 v179, 0xffff0000, v179
	v_pk_fma_f32 v[108:109], v[108:109], v[120:121], v[160:161]
	v_pk_fma_f32 v[110:111], v[110:111], v[122:123], v[178:179]
	v_add_u32_e32 v216, 0x8000, v213
	v_cvt_pk_bf16_f32 v108, v108, v109
	v_cvt_pk_bf16_f32 v109, v110, v111
	global_store_dwordx2 v216, v[108:109], s[18:19] offset:0
	global_load_dwordx2 v[178:179], v215, s[16:17] offset:256
	global_load_dwordx2 v[112:113], v215, s[16:17] offset:288
	s_waitcnt vmcnt(31)
	v_lshlrev_b32_e32 v160, 16, v180
	v_and_b32_e32 v161, 0xffff0000, v180
	v_lshlrev_b32_e32 v180, 16, v181
	v_and_b32_e32 v181, 0xffff0000, v181
	v_pk_fma_f32 v[104:105], v[104:105], v[128:129], v[160:161]
	v_pk_fma_f32 v[106:107], v[106:107], v[130:131], v[180:181]
	v_cvt_pk_bf16_f32 v104, v104, v105
	v_cvt_pk_bf16_f32 v105, v106, v107
	global_store_dwordx2 v216, v[104:105], s[18:19] offset:32
	s_waitcnt vmcnt(31)
	v_lshlrev_b32_e32 v160, 16, v182
	v_and_b32_e32 v161, 0xffff0000, v182
	v_lshlrev_b32_e32 v182, 16, v183
	v_and_b32_e32 v183, 0xffff0000, v183
	v_pk_fma_f32 v[100:101], v[100:101], v[136:137], v[160:161]
	v_pk_fma_f32 v[102:103], v[102:103], v[138:139], v[182:183]
	v_cvt_pk_bf16_f32 v100, v100, v101
	v_cvt_pk_bf16_f32 v101, v102, v103
	global_store_dwordx2 v216, v[100:101], s[18:19] offset:256
	s_waitcnt vmcnt(31)
; __device__ __forceinline__ unsigned cvt_pk_bf16(float lo, float hi) { unsigned r; asm volatile("v_cvt_pk_bf16_f32 %0, %1, %2" : "=v"(r) : "v"(lo), "v"(hi)); return r; }
;     __device__ __forceinline__ void operator()(const f32x4 (&acc)[2][2][4][2], const Unit& u, int wr, int wc, int fr, int fq) const {
;         int row0 = u.pm * BM + wr * 64 + fr + row_off; const bool isctx = row0 >= NLAT; const int b = isctx ? 8 : (row0 >> 12);
;         const void* bp = isctx ? base_ctx : base_lat; void* op = isctx ? out_ctx : out_lat; if (isctx) row0 -= NLAT;
;         const int col0 = u.pn * BM + wc * 32 + 4 * fq;
;         f32x4 gv[2][2];
; #pragma unroll
;         for (int bj = 0; bj < 2; ++bj)
; #pragma unroll
;             for (int n = 0; n < 2; ++n) gv[bj][n] = *(const f32x4*)(gate + b * MODS + col0 + bj * HALF + n * 16);
; #pragma unroll
;         for (int ai = 0; ai < 2; ++ai)
; #pragma unroll
;             for (int m = 0; m < 4; ++m) { const size_t off = (size_t)(row0 + ai * HALF + m * 16) * DM + col0;
; #pragma unroll
;                 for (int bj = 0; bj < 2; ++bj)
; #pragma unroll
;                     for (int n = 0; n < 2; ++n) { const size_t o2 = off + bj * HALF + n * 16; f32x4 bs;
;                         if (BB) { const u32x2 r = *(const u32x2*)((const bf16_t*)bp + o2); bs = (f32x4){__uint_as_float(r.x << 16), __uint_as_float(r.x & 0xffff0000u), __uint_as_float(r.y << 16), __uint_as_float(r.y & 0xffff0000u)}; }
;                         else bs = *(const f32x4*)((const float*)bp + o2);
;                         const f32x4 o = bs + gv[bj][n] * acc[ai][bj][m][n];
;                         if (OB) { u32x2 w; w.x = cvt_pk_bf16(o[0], o[1]); w.y = cvt_pk_bf16(o[2], o[3]); *(u32x2*)((bf16_t*)op + o2) = w; }
;                         else *(f32x4*)((float*)op + o2) = o; } }
;     }
	v_lshlrev_b32_e32 v160, 16, v184
	v_and_b32_e32 v161, 0xffff0000, v184
	v_lshlrev_b32_e32 v184, 16, v185
	v_and_b32_e32 v185, 0xffff0000, v185
	v_pk_fma_f32 v[96:97], v[96:97], v[140:141], v[160:161]
	v_pk_fma_f32 v[98:99], v[98:99], v[142:143], v[184:185]
	v_cvt_pk_bf16_f32 v96, v96, v97
	v_cvt_pk_bf16_f32 v97, v98, v99
	global_store_dwordx2 v216, v[96:97], s[18:19] offset:288
	s_waitcnt vmcnt(31)
	v_lshlrev_b32_e32 v160, 16, v186
	v_and_b32_e32 v161, 0xffff0000, v186
	v_lshlrev_b32_e32 v186, 16, v187
	v_and_b32_e32 v187, 0xffff0000, v187
	v_pk_fma_f32 v[92:93], v[92:93], v[120:121], v[160:161]
	v_pk_fma_f32 v[94:95], v[94:95], v[122:123], v[186:187]
	v_add_u32_e32 v216, 0x10000, v213
	v_cvt_pk_bf16_f32 v92, v92, v93
	v_cvt_pk_bf16_f32 v93, v94, v95
	global_store_dwordx2 v216, v[92:93], s[18:19] offset:0
	s_waitcnt vmcnt(31)
	v_lshlrev_b32_e32 v160, 16, v190
	v_and_b32_e32 v161, 0xffff0000, v190
	v_lshlrev_b32_e32 v190, 16, v191
	v_and_b32_e32 v191, 0xffff0000, v191
	v_pk_fma_f32 v[88:89], v[88:89], v[128:129], v[160:161]
	v_pk_fma_f32 v[90:91], v[90:91], v[130:131], v[190:191]
	v_cvt_pk_bf16_f32 v88, v88, v89
	v_cvt_pk_bf16_f32 v89, v90, v91
	global_store_dwordx2 v216, v[88:89], s[18:19] offset:32
	s_waitcnt vmcnt(31)
	v_lshlrev_b32_e32 v160, 16, v192
	v_and_b32_e32 v161, 0xffff0000, v192
	v_lshlrev_b32_e32 v192, 16, v193
	v_and_b32_e32 v193, 0xffff0000, v193
	v_pk_fma_f32 v[84:85], v[84:85], v[136:137], v[160:161]
	v_pk_fma_f32 v[86:87], v[86:87], v[138:139], v[192:193]
	v_cvt_pk_bf16_f32 v84, v84, v85
	v_cvt_pk_bf16_f32 v85, v86, v87
	global_store_dwordx2 v216, v[84:85], s[18:19] offset:256
	s_waitcnt vmcnt(31)
	v_lshlrev_b32_e32 v160, 16, v194
	v_and_b32_e32 v161, 0xffff0000, v194
	v_lshlrev_b32_e32 v194, 16, v195
	v_and_b32_e32 v195, 0xffff0000, v195
	v_pk_fma_f32 v[80:81], v[80:81], v[140:141], v[160:161]
	v_pk_fma_f32 v[82:83], v[82:83], v[142:143], v[194:195]
	v_cvt_pk_bf16_f32 v80, v80, v81
	v_cvt_pk_bf16_f32 v81, v82, v83
	global_store_dwordx2 v216, v[80:81], s[18:19] offset:288
	s_waitcnt vmcnt(31)
	v_lshlrev_b32_e32 v160, 16, v196
	v_and_b32_e32 v161, 0xffff0000, v196
	v_lshlrev_b32_e32 v196, 16, v197
	v_and_b32_e32 v197, 0xffff0000, v197
	v_pk_fma_f32 v[76:77], v[76:77], v[120:121], v[160:161]
	v_pk_fma_f32 v[78:79], v[78:79], v[122:123], v[196:197]
	v_add_u32_e32 v216, 0x18000, v213
	v_cvt_pk_bf16_f32 v76, v76, v77
	v_cvt_pk_bf16_f32 v77, v78, v79
	global_store_dwordx2 v216, v[76:77], s[18:19] offset:0
	s_waitcnt vmcnt(31)
	v_lshlrev_b32_e32 v160, 16, v198
	v_and_b32_e32 v161, 0xffff0000, v198
	v_lshlrev_b32_e32 v198, 16, v199
	v_and_b32_e32 v199, 0xffff0000, v199
	v_pk_fma_f32 v[72:73], v[72:73], v[128:129], v[160:161]
	v_pk_fma_f32 v[74:75], v[74:75], v[130:131], v[198:199]
	v_cvt_pk_bf16_f32 v72, v72, v73
	v_cvt_pk_bf16_f32 v73, v74, v75
	global_store_dwordx2 v216, v[72:73], s[18:19] offset:32
	s_waitcnt vmcnt(31)
	v_lshlrev_b32_e32 v160, 16, v200
	v_and_b32_e32 v161, 0xffff0000, v200
	v_lshlrev_b32_e32 v200, 16, v201
	v_and_b32_e32 v201, 0xffff0000, v201
	v_pk_fma_f32 v[68:69], v[68:69], v[136:137], v[160:161]
	v_pk_fma_f32 v[70:71], v[70:71], v[138:139], v[200:201]
	v_cvt_pk_bf16_f32 v68, v68, v69
	v_cvt_pk_bf16_f32 v69, v70, v71
	global_store_dwordx2 v216, v[68:69], s[18:19] offset:256
	s_waitcnt vmcnt(31)
	v_lshlrev_b32_e32 v160, 16, v202
	v_and_b32_e32 v161, 0xffff0000, v202
	v_lshlrev_b32_e32 v202, 16, v203
	v_and_b32_e32 v203, 0xffff0000, v203
	v_pk_fma_f32 v[64:65], v[64:65], v[140:141], v[160:161]
	v_pk_fma_f32 v[66:67], v[66:67], v[142:143], v[202:203]
	v_cvt_pk_bf16_f32 v64, v64, v65
	v_cvt_pk_bf16_f32 v65, v66, v67
	global_store_dwordx2 v216, v[64:65], s[18:19] offset:288
	s_waitcnt vmcnt(31)
	v_lshlrev_b32_e32 v160, 16, v204
	v_and_b32_e32 v161, 0xffff0000, v204
	v_lshlrev_b32_e32 v204, 16, v205
	v_and_b32_e32 v205, 0xffff0000, v205
	v_pk_fma_f32 v[60:61], v[60:61], v[120:121], v[160:161]
	v_pk_fma_f32 v[62:63], v[62:63], v[122:123], v[204:205]
	v_add_u32_e32 v216, 0x40000, v213
	v_cvt_pk_bf16_f32 v60, v60, v61
	v_cvt_pk_bf16_f32 v61, v62, v63
	global_store_dwordx2 v216, v[60:61], s[18:19] offset:0
	s_waitcnt vmcnt(31)
	v_lshlrev_b32_e32 v160, 16, v206
	v_and_b32_e32 v161, 0xffff0000, v206
	v_lshlrev_b32_e32 v206, 16, v207
	v_and_b32_e32 v207, 0xffff0000, v207
	v_pk_fma_f32 v[56:57], v[56:57], v[128:129], v[160:161]
	v_pk_fma_f32 v[58:59], v[58:59], v[130:131], v[206:207]
	v_cvt_pk_bf16_f32 v56, v56, v57
	v_cvt_pk_bf16_f32 v57, v58, v59
	global_store_dwordx2 v216, v[56:57], s[18:19] offset:32
	s_waitcnt vmcnt(31)
	v_lshlrev_b32_e32 v160, 16, v208
	v_and_b32_e32 v161, 0xffff0000, v208
	v_lshlrev_b32_e32 v208, 16, v209
	v_and_b32_e32 v209, 0xffff0000, v209
	v_pk_fma_f32 v[52:53], v[52:53], v[136:137], v[160:161]
	v_pk_fma_f32 v[54:55], v[54:55], v[138:139], v[208:209]
	v_cvt_pk_bf16_f32 v52, v52, v53
	v_cvt_pk_bf16_f32 v53, v54, v55
	global_store_dwordx2 v216, v[52:53], s[18:19] offset:256
	s_waitcnt vmcnt(31)
	v_lshlrev_b32_e32 v160, 16, v210
	v_and_b32_e32 v161, 0xffff0000, v210
	v_lshlrev_b32_e32 v210, 16, v211
	v_and_b32_e32 v211, 0xffff0000, v211
	v_pk_fma_f32 v[48:49], v[48:49], v[140:141], v[160:161]
	v_pk_fma_f32 v[50:51], v[50:51], v[142:143], v[210:211]
	v_cvt_pk_bf16_f32 v48, v48, v49
	v_cvt_pk_bf16_f32 v49, v50, v51
	global_store_dwordx2 v216, v[48:49], s[18:19] offset:288
	s_waitcnt vmcnt(30)
; __device__ __forceinline__ unsigned cvt_pk_bf16(float lo, float hi) { unsigned r; asm volatile("v_cvt_pk_bf16_f32 %0, %1, %2" : "=v"(r) : "v"(lo), "v"(hi)); return r; }
;     __device__ __forceinline__ void operator()(const f32x4 (&acc)[2][2][4][2], const Unit& u, int wr, int wc, int fr, int fq) const {
;         int row0 = u.pm * BM + wr * 64 + fr + row_off; const bool isctx = row0 >= NLAT; const int b = isctx ? 8 : (row0 >> 12);
;         const void* bp = isctx ? base_ctx : base_lat; void* op = isctx ? out_ctx : out_lat; if (isctx) row0 -= NLAT;
;         const int col0 = u.pn * BM + wc * 32 + 4 * fq;
;         f32x4 gv[2][2];
; #pragma unroll
;         for (int bj = 0; bj < 2; ++bj)
; #pragma unroll
;             for (int n = 0; n < 2; ++n) gv[bj][n] = *(const f32x4*)(gate + b * MODS + col0 + bj * HALF + n * 16);
; #pragma unroll
;         for (int ai = 0; ai < 2; ++ai)
; #pragma unroll
;             for (int m = 0; m < 4; ++m) { const size_t off = (size_t)(row0 + ai * HALF + m * 16) * DM + col0;
; #pragma unroll
;                 for (int bj = 0; bj < 2; ++bj)
; #pragma unroll
;                     for (int n = 0; n < 2; ++n) { const size_t o2 = off + bj * HALF + n * 16; f32x4 bs;
;                         if (BB) { const u32x2 r = *(const u32x2*)((const bf16_t*)bp + o2); bs = (f32x4){__uint_as_float(r.x << 16), __uint_as_float(r.x & 0xffff0000u), __uint_as_float(r.y << 16), __uint_as_float(r.y & 0xffff0000u)}; }
;                         else bs = *(const f32x4*)((const float*)bp + o2);
;                         const f32x4 o = bs + gv[bj][n] * acc[ai][bj][m][n];
;                         if (OB) { u32x2 w; w.x = cvt_pk_bf16(o[0], o[1]); w.y = cvt_pk_bf16(o[2], o[3]); *(u32x2*)((bf16_t*)op + o2) = w; }
;                         else *(f32x4*)((float*)op + o2) = o; } }
;     }
	v_lshlrev_b32_e32 v160, 16, v162
	v_and_b32_e32 v161, 0xffff0000, v162
	v_lshlrev_b32_e32 v162, 16, v163
	v_and_b32_e32 v163, 0xffff0000, v163
	v_pk_fma_f32 v[44:45], v[44:45], v[120:121], v[160:161]
	v_pk_fma_f32 v[46:47], v[46:47], v[122:123], v[162:163]
	v_add_u32_e32 v216, 0x48000, v213
	v_cvt_pk_bf16_f32 v44, v44, v45
	v_cvt_pk_bf16_f32 v45, v46, v47
	global_store_dwordx2 v216, v[44:45], s[18:19] offset:0
	s_waitcnt vmcnt(29)
	v_lshlrev_b32_e32 v160, 16, v172
	v_and_b32_e32 v161, 0xffff0000, v172
	v_lshlrev_b32_e32 v172, 16, v173
	v_and_b32_e32 v173, 0xffff0000, v173
	v_pk_fma_f32 v[40:41], v[40:41], v[128:129], v[160:161]
	v_pk_fma_f32 v[42:43], v[42:43], v[130:131], v[172:173]
	v_cvt_pk_bf16_f32 v40, v40, v41
	v_cvt_pk_bf16_f32 v41, v42, v43
	global_store_dwordx2 v216, v[40:41], s[18:19] offset:32
	s_waitcnt vmcnt(29)
	v_lshlrev_b32_e32 v160, 16, v132
	v_and_b32_e32 v161, 0xffff0000, v132
	v_lshlrev_b32_e32 v132, 16, v133
	v_and_b32_e32 v133, 0xffff0000, v133
	v_pk_fma_f32 v[36:37], v[36:37], v[136:137], v[160:161]
	v_pk_fma_f32 v[38:39], v[38:39], v[138:139], v[132:133]
	v_cvt_pk_bf16_f32 v36, v36, v37
	v_cvt_pk_bf16_f32 v37, v38, v39
	global_store_dwordx2 v216, v[36:37], s[18:19] offset:256
	s_waitcnt vmcnt(29)
	v_lshlrev_b32_e32 v160, 16, v134
	v_and_b32_e32 v161, 0xffff0000, v134
	v_lshlrev_b32_e32 v134, 16, v135
	v_and_b32_e32 v135, 0xffff0000, v135
	v_pk_fma_f32 v[32:33], v[32:33], v[140:141], v[160:161]
	v_pk_fma_f32 v[34:35], v[34:35], v[142:143], v[134:135]
	v_cvt_pk_bf16_f32 v32, v32, v33
	v_cvt_pk_bf16_f32 v33, v34, v35
	global_store_dwordx2 v216, v[32:33], s[18:19] offset:288
	s_waitcnt vmcnt(28)
	v_lshlrev_b32_e32 v160, 16, v174
	v_and_b32_e32 v161, 0xffff0000, v174
	v_lshlrev_b32_e32 v174, 16, v175
	v_and_b32_e32 v175, 0xffff0000, v175
	v_pk_fma_f32 v[28:29], v[28:29], v[120:121], v[160:161]
	v_pk_fma_f32 v[30:31], v[30:31], v[122:123], v[174:175]
	v_add_u32_e32 v216, 0x50000, v213
	v_cvt_pk_bf16_f32 v28, v28, v29
	v_cvt_pk_bf16_f32 v29, v30, v31
	global_store_dwordx2 v216, v[28:29], s[18:19] offset:0
	s_waitcnt vmcnt(28)
	v_lshlrev_b32_e32 v160, 16, v124
	v_and_b32_e32 v161, 0xffff0000, v124
	v_lshlrev_b32_e32 v124, 16, v125
	v_and_b32_e32 v125, 0xffff0000, v125
	v_pk_fma_f32 v[24:25], v[24:25], v[128:129], v[160:161]
	v_pk_fma_f32 v[26:27], v[26:27], v[130:131], v[124:125]
	v_cvt_pk_bf16_f32 v24, v24, v25
	v_cvt_pk_bf16_f32 v25, v26, v27
	global_store_dwordx2 v216, v[24:25], s[18:19] offset:32
	s_waitcnt vmcnt(28)
	v_lshlrev_b32_e32 v160, 16, v126
	v_and_b32_e32 v161, 0xffff0000, v126
	v_lshlrev_b32_e32 v126, 16, v127
	v_and_b32_e32 v127, 0xffff0000, v127
	v_pk_fma_f32 v[20:21], v[20:21], v[136:137], v[160:161]
	v_pk_fma_f32 v[22:23], v[22:23], v[138:139], v[126:127]
	v_cvt_pk_bf16_f32 v20, v20, v21
	v_cvt_pk_bf16_f32 v21, v22, v23
	global_store_dwordx2 v216, v[20:21], s[18:19] offset:256
	s_waitcnt vmcnt(27)
	v_lshlrev_b32_e32 v160, 16, v176
	v_and_b32_e32 v161, 0xffff0000, v176
	v_lshlrev_b32_e32 v176, 16, v177
	v_and_b32_e32 v177, 0xffff0000, v177
	v_pk_fma_f32 v[16:17], v[16:17], v[140:141], v[160:161]
	v_pk_fma_f32 v[18:19], v[18:19], v[142:143], v[176:177]
	v_cvt_pk_bf16_f32 v16, v16, v17
	v_cvt_pk_bf16_f32 v17, v18, v19
	global_store_dwordx2 v216, v[16:17], s[18:19] offset:288
	s_waitcnt vmcnt(27)
	v_lshlrev_b32_e32 v160, 16, v116
	v_and_b32_e32 v161, 0xffff0000, v116
	v_lshlrev_b32_e32 v116, 16, v117
	v_and_b32_e32 v117, 0xffff0000, v117
	v_pk_fma_f32 v[12:13], v[12:13], v[120:121], v[160:161]
	v_pk_fma_f32 v[14:15], v[14:15], v[122:123], v[116:117]
	v_add_u32_e32 v216, 0x58000, v213
	v_cvt_pk_bf16_f32 v12, v12, v13
	v_cvt_pk_bf16_f32 v13, v14, v15
	global_store_dwordx2 v216, v[12:13], s[18:19] offset:0
	s_waitcnt vmcnt(27)
	v_lshlrev_b32_e32 v160, 16, v118
	v_and_b32_e32 v161, 0xffff0000, v118
	v_lshlrev_b32_e32 v118, 16, v119
	v_and_b32_e32 v119, 0xffff0000, v119
	v_pk_fma_f32 v[8:9], v[8:9], v[128:129], v[160:161]
	v_pk_fma_f32 v[10:11], v[10:11], v[130:131], v[118:119]
	v_cvt_pk_bf16_f32 v8, v8, v9
	v_cvt_pk_bf16_f32 v9, v10, v11
	global_store_dwordx2 v216, v[8:9], s[18:19] offset:32
	s_waitcnt vmcnt(26)
	v_lshlrev_b32_e32 v160, 16, v178
	v_and_b32_e32 v161, 0xffff0000, v178
	v_lshlrev_b32_e32 v178, 16, v179
	v_and_b32_e32 v179, 0xffff0000, v179
	v_pk_fma_f32 v[4:5], v[4:5], v[136:137], v[160:161]
	v_pk_fma_f32 v[6:7], v[6:7], v[138:139], v[178:179]
	v_cvt_pk_bf16_f32 v4, v4, v5
	v_cvt_pk_bf16_f32 v5, v6, v7
	global_store_dwordx2 v216, v[4:5], s[18:19] offset:256
	s_waitcnt vmcnt(26)
	v_lshlrev_b32_e32 v160, 16, v112
	v_and_b32_e32 v161, 0xffff0000, v112
	v_lshlrev_b32_e32 v112, 16, v113
	v_and_b32_e32 v113, 0xffff0000, v113
	v_pk_fma_f32 v[0:1], v[0:1], v[140:141], v[160:161]
	v_pk_fma_f32 v[2:3], v[2:3], v[142:143], v[112:113]
	v_cvt_pk_bf16_f32 v0, v0, v1
	v_cvt_pk_bf16_f32 v1, v2, v3
	global_store_dwordx2 v216, v[0:1], s[18:19] offset:288
	s_movk_i32 s8, 0x7fff
	s_mov_b64 s[8:9], 0x40000
	s_and_b64 vcc, exec, s[6:7]
	s_mov_b64 s[6:7], -1
	s_cbranch_vccnz .LBB0_1668
	s_andn2_b64 vcc, exec, s[14:15]
	s_cbranch_vccnz .LBB0_1667
	s_barrier
	s_branch .LBB0_1667

; __device__ __forceinline__ unsigned cvt_pk_bf16(float lo, float hi) { unsigned r; asm volatile("v_cvt_pk_bf16_f32 %0, %1, %2" : "=v"(r) : "v"(lo), "v"(hi)); return r; }
;     __device__ __forceinline__ void operator()(const f32x4 (&acc)[2][2][4][2], const Unit& u, int wr, int wc, int fr, int fq) const {
;         int row0 = u.pm * BM + wr * 64 + fr + row_off; const bool isctx = row0 >= NLAT; const int b = isctx ? 8 : (row0 >> 12);
;         const void* bp = isctx ? base_ctx : base_lat; void* op = isctx ? out_ctx : out_lat; if (isctx) row0 -= NLAT;
;         const int col0 = u.pn * BM + wc * 32 + 4 * fq;
;         f32x4 gv[2][2];
; #pragma unroll
;         for (int bj = 0; bj < 2; ++bj)
; #pragma unroll
;             for (int n = 0; n < 2; ++n) gv[bj][n] = *(const f32x4*)(gate + b * MODS + col0 + bj * HALF + n * 16);
; #pragma unroll
;         for (int ai = 0; ai < 2; ++ai)
; #pragma unroll
;             for (int m = 0; m < 4; ++m) { const size_t off = (size_t)(row0 + ai * HALF + m * 16) * DM + col0;
; #pragma unroll
;                 for (int bj = 0; bj < 2; ++bj)
; #pragma unroll
;                     for (int n = 0; n < 2; ++n) { const size_t o2 = off + bj * HALF + n * 16; f32x4 bs;
;                         if (BB) { const u32x2 r = *(const u32x2*)((const bf16_t*)bp + o2); bs = (f32x4){__uint_as_float(r.x << 16), __uint_as_float(r.x & 0xffff0000u), __uint_as_float(r.y << 16), __uint_as_float(r.y & 0xffff0000u)}; }
;                         else bs = *(const f32x4*)((const float*)bp + o2);
;                         const f32x4 o = bs + gv[bj][n] * acc[ai][bj][m][n];
;                         if (OB) { u32x2 w; w.x = cvt_pk_bf16(o[0], o[1]); w.y = cvt_pk_bf16(o[2], o[3]); *(u32x2*)((bf16_t*)op + o2) = w; }
;                         else *(f32x4*)((float*)op + o2) = o; } }
;     }
.LBB0_1900:
	s_waitcnt lgkmcnt(0)
	v_lshl_add_u32 v213, s59, 8, v166
	v_lshl_or_b32 v212, s60, 8, v168
	v_lshlrev_b32_e32 v210, 11, v213
	v_lshlrev_b32_e32 v211, 12, v213
	v_lshl_add_u32 v210, v212, 1, v210
	v_lshl_add_u32 v211, v212, 2, v211
	v_mov_b32_e32 v214, s59
	v_lshrrev_b32_e32 v214, 4, v214
	v_mul_u32_u24_e32 v214, 0x1800, v214
	v_add_lshl_u32 v212, v212, v214, 2
	global_load_dwordx4 v[128:131], v212, s[16:17] offset:0
	global_load_dwordx4 v[132:135], v212, s[16:17] offset:64
	global_load_dwordx4 v[136:139], v212, s[16:17] offset:512
	global_load_dwordx4 v[140:143], v212, s[16:17] offset:576
	v_mov_b32_e32 v213, v210
	global_load_dwordx2 v[162:163], v213, s[14:15] offset:0
	global_load_dwordx2 v[172:173], v213, s[14:15] offset:32
	global_load_dwordx2 v[174:175], v213, s[14:15] offset:256
	global_load_dwordx2 v[176:177], v213, s[14:15] offset:288
	v_add_u32_e32 v213, 0x8000, v210
	global_load_dwordx2 v[178:179], v213, s[14:15] offset:0
	global_load_dwordx2 v[180:181], v213, s[14:15] offset:32
	global_load_dwordx2 v[182:183], v213, s[14:15] offset:256
	global_load_dwordx2 v[184:185], v213, s[14:15] offset:288
	v_add_u32_e32 v213, 0x10000, v210
	global_load_dwordx2 v[186:187], v213, s[14:15] offset:0
	global_load_dwordx2 v[188:189], v213, s[14:15] offset:32
	global_load_dwordx2 v[190:191], v213, s[14:15] offset:256
	global_load_dwordx2 v[192:193], v213, s[14:15] offset:288
	v_add_u32_e32 v213, 0x18000, v210
	global_load_dwordx2 v[194:195], v213, s[14:15] offset:0
	global_load_dwordx2 v[196:197], v213, s[14:15] offset:32
	global_load_dwordx2 v[198:199], v213, s[14:15] offset:256
	global_load_dwordx2 v[200:201], v213, s[14:15] offset:288
	v_add_u32_e32 v213, 0x40000, v210
	global_load_dwordx2 v[202:203], v213, s[14:15] offset:0
	global_load_dwordx2 v[204:205], v213, s[14:15] offset:32
	global_load_dwordx2 v[206:207], v213, s[14:15] offset:256
	global_load_dwordx2 v[208:209], v213, s[14:15] offset:288
	s_waitcnt vmcnt(19)
	v_lshlrev_b32_e32 v160, 16, v162
	v_and_b32_e32 v161, 0xffff0000, v162
	v_lshlrev_b32_e32 v162, 16, v163
	v_and_b32_e32 v163, 0xffff0000, v163
	v_pk_fma_f32 v[124:125], v[124:125], v[128:129], v[160:161]
	v_pk_fma_f32 v[126:127], v[126:127], v[130:131], v[162:163]
	v_mov_b32_e32 v214, v211
	global_store_dwordx4 v214, v[124:127], s[10:11] offset:0
	v_add_u32_e32 v213, 0x48000, v210
	global_load_dwordx2 v[162:163], v213, s[14:15] offset:0
	s_waitcnt vmcnt(20)
	v_lshlrev_b32_e32 v160, 16, v172
	v_and_b32_e32 v161, 0xffff0000, v172
	v_lshlrev_b32_e32 v172, 16, v173
	v_and_b32_e32 v173, 0xffff0000, v173
	v_pk_fma_f32 v[120:121], v[120:121], v[132:133], v[160:161]
	v_pk_fma_f32 v[122:123], v[122:123], v[134:135], v[172:173]
	global_store_dwordx4 v214, v[120:123], s[10:11] offset:64
	global_load_dwordx2 v[172:173], v213, s[14:15] offset:32
	global_load_dwordx2 v[124:125], v213, s[14:15] offset:256
	global_load_dwordx2 v[126:127], v213, s[14:15] offset:288
	s_waitcnt vmcnt(23)
	v_lshlrev_b32_e32 v160, 16, v174
	v_and_b32_e32 v161, 0xffff0000, v174
	v_lshlrev_b32_e32 v174, 16, v175
	v_and_b32_e32 v175, 0xffff0000, v175
	v_pk_fma_f32 v[116:117], v[116:117], v[136:137], v[160:161]
	v_pk_fma_f32 v[118:119], v[118:119], v[138:139], v[174:175]
	global_store_dwordx4 v214, v[116:119], s[10:11] offset:512
	v_add_u32_e32 v213, 0x50000, v210
	global_load_dwordx2 v[174:175], v213, s[14:15] offset:0
	global_load_dwordx2 v[120:121], v213, s[14:15] offset:32
	global_load_dwordx2 v[122:123], v213, s[14:15] offset:256
	s_waitcnt vmcnt(26)
	v_lshlrev_b32_e32 v160, 16, v176
	v_and_b32_e32 v161, 0xffff0000, v176
	v_lshlrev_b32_e32 v176, 16, v177
	v_and_b32_e32 v177, 0xffff0000, v177
	v_pk_fma_f32 v[112:113], v[112:113], v[140:141], v[160:161]
	v_pk_fma_f32 v[114:115], v[114:115], v[142:143], v[176:177]
	global_store_dwordx4 v214, v[112:115], s[10:11] offset:576
	global_load_dwordx2 v[176:177], v213, s[14:15] offset:288
	v_add_u32_e32 v213, 0x58000, v210
	global_load_dwordx2 v[116:117], v213, s[14:15] offset:0
	global_load_dwordx2 v[118:119], v213, s[14:15] offset:32
	s_waitcnt vmcnt(29)
	v_lshlrev_b32_e32 v160, 16, v178
	v_and_b32_e32 v161, 0xffff0000, v178
	v_lshlrev_b32_e32 v178, 16, v179
	v_and_b32_e32 v179, 0xffff0000, v179
	v_pk_fma_f32 v[108:109], v[108:109], v[128:129], v[160:161]
	v_pk_fma_f32 v[110:111], v[110:111], v[130:131], v[178:179]
	v_add_u32_e32 v214, 0x10000, v211
	global_store_dwordx4 v214, v[108:111], s[10:11] offset:0
	global_load_dwordx2 v[178:179], v213, s[14:15] offset:256
	global_load_dwordx2 v[112:113], v213, s[14:15] offset:288
	s_waitcnt vmcnt(31)
	v_lshlrev_b32_e32 v160, 16, v180
	v_and_b32_e32 v161, 0xffff0000, v180
	v_lshlrev_b32_e32 v180, 16, v181
	v_and_b32_e32 v181, 0xffff0000, v181
	v_pk_fma_f32 v[104:105], v[104:105], v[132:133], v[160:161]
	v_pk_fma_f32 v[106:107], v[106:107], v[134:135], v[180:181]
	global_store_dwordx4 v214, v[104:107], s[10:11] offset:64
	s_waitcnt vmcnt(31)
	v_lshlrev_b32_e32 v160, 16, v182
	v_and_b32_e32 v161, 0xffff0000, v182
	v_lshlrev_b32_e32 v182, 16, v183
	v_and_b32_e32 v183, 0xffff0000, v183
	v_pk_fma_f32 v[100:101], v[100:101], v[136:137], v[160:161]
	v_pk_fma_f32 v[102:103], v[102:103], v[138:139], v[182:183]
	global_store_dwordx4 v214, v[100:103], s[10:11] offset:512
	s_waitcnt vmcnt(31)
	v_lshlrev_b32_e32 v160, 16, v184
	v_and_b32_e32 v161, 0xffff0000, v184
	v_lshlrev_b32_e32 v184, 16, v185
	v_and_b32_e32 v185, 0xffff0000, v185
	v_pk_fma_f32 v[96:97], v[96:97], v[140:141], v[160:161]
	v_pk_fma_f32 v[98:99], v[98:99], v[142:143], v[184:185]
	global_store_dwordx4 v214, v[96:99], s[10:11] offset:576
	s_waitcnt vmcnt(31)
; __device__ __forceinline__ unsigned cvt_pk_bf16(float lo, float hi) { unsigned r; asm volatile("v_cvt_pk_bf16_f32 %0, %1, %2" : "=v"(r) : "v"(lo), "v"(hi)); return r; }
;     __device__ __forceinline__ void operator()(const f32x4 (&acc)[2][2][4][2], const Unit& u, int wr, int wc, int fr, int fq) const {
;         int row0 = u.pm * BM + wr * 64 + fr + row_off; const bool isctx = row0 >= NLAT; const int b = isctx ? 8 : (row0 >> 12);
;         const void* bp = isctx ? base_ctx : base_lat; void* op = isctx ? out_ctx : out_lat; if (isctx) row0 -= NLAT;
;         const int col0 = u.pn * BM + wc * 32 + 4 * fq;
;         f32x4 gv[2][2];
; #pragma unroll
;         for (int bj = 0; bj < 2; ++bj)
; #pragma unroll
;             for (int n = 0; n < 2; ++n) gv[bj][n] = *(const f32x4*)(gate + b * MODS + col0 + bj * HALF + n * 16);
; #pragma unroll
;         for (int ai = 0; ai < 2; ++ai)
; #pragma unroll
;             for (int m = 0; m < 4; ++m) { const size_t off = (size_t)(row0 + ai * HALF + m * 16) * DM + col0;
; #pragma unroll
;                 for (int bj = 0; bj < 2; ++bj)
; #pragma unroll
;                     for (int n = 0; n < 2; ++n) { const size_t o2 = off + bj * HALF + n * 16; f32x4 bs;
;                         if (BB) { const u32x2 r = *(const u32x2*)((const bf16_t*)bp + o2); bs = (f32x4){__uint_as_float(r.x << 16), __uint_as_float(r.x & 0xffff0000u), __uint_as_float(r.y << 16), __uint_as_float(r.y & 0xffff0000u)}; }
;                         else bs = *(const f32x4*)((const float*)bp + o2);
;                         const f32x4 o = bs + gv[bj][n] * acc[ai][bj][m][n];
;                         if (OB) { u32x2 w; w.x = cvt_pk_bf16(o[0], o[1]); w.y = cvt_pk_bf16(o[2], o[3]); *(u32x2*)((bf16_t*)op + o2) = w; }
;                         else *(f32x4*)((float*)op + o2) = o; } }
;     }
	v_lshlrev_b32_e32 v160, 16, v186
	v_and_b32_e32 v161, 0xffff0000, v186
	v_lshlrev_b32_e32 v186, 16, v187
	v_and_b32_e32 v187, 0xffff0000, v187
	v_pk_fma_f32 v[92:93], v[92:93], v[128:129], v[160:161]
	v_pk_fma_f32 v[94:95], v[94:95], v[130:131], v[186:187]
	v_add_u32_e32 v214, 0x20000, v211
	global_store_dwordx4 v214, v[92:95], s[10:11] offset:0
	s_waitcnt vmcnt(31)
	v_lshlrev_b32_e32 v160, 16, v188
	v_and_b32_e32 v161, 0xffff0000, v188
	v_lshlrev_b32_e32 v188, 16, v189
	v_and_b32_e32 v189, 0xffff0000, v189
	v_pk_fma_f32 v[88:89], v[88:89], v[132:133], v[160:161]
	v_pk_fma_f32 v[90:91], v[90:91], v[134:135], v[188:189]
	global_store_dwordx4 v214, v[88:91], s[10:11] offset:64
	s_waitcnt vmcnt(31)
	v_lshlrev_b32_e32 v160, 16, v190
	v_and_b32_e32 v161, 0xffff0000, v190
	v_lshlrev_b32_e32 v190, 16, v191
	v_and_b32_e32 v191, 0xffff0000, v191
	v_pk_fma_f32 v[84:85], v[84:85], v[136:137], v[160:161]
	v_pk_fma_f32 v[86:87], v[86:87], v[138:139], v[190:191]
	global_store_dwordx4 v214, v[84:87], s[10:11] offset:512
	s_waitcnt vmcnt(31)
	v_lshlrev_b32_e32 v160, 16, v192
	v_and_b32_e32 v161, 0xffff0000, v192
	v_lshlrev_b32_e32 v192, 16, v193
	v_and_b32_e32 v193, 0xffff0000, v193
	v_pk_fma_f32 v[80:81], v[80:81], v[140:141], v[160:161]
	v_pk_fma_f32 v[82:83], v[82:83], v[142:143], v[192:193]
	global_store_dwordx4 v214, v[80:83], s[10:11] offset:576
	s_waitcnt vmcnt(31)
	v_lshlrev_b32_e32 v160, 16, v194
	v_and_b32_e32 v161, 0xffff0000, v194
	v_lshlrev_b32_e32 v194, 16, v195
	v_and_b32_e32 v195, 0xffff0000, v195
	v_pk_fma_f32 v[76:77], v[76:77], v[128:129], v[160:161]
	v_pk_fma_f32 v[78:79], v[78:79], v[130:131], v[194:195]
	v_add_u32_e32 v214, 0x30000, v211
	global_store_dwordx4 v214, v[76:79], s[10:11] offset:0
	s_waitcnt vmcnt(31)
	v_lshlrev_b32_e32 v160, 16, v196
	v_and_b32_e32 v161, 0xffff0000, v196
	v_lshlrev_b32_e32 v196, 16, v197
	v_and_b32_e32 v197, 0xffff0000, v197
	v_pk_fma_f32 v[72:73], v[72:73], v[132:133], v[160:161]
	v_pk_fma_f32 v[74:75], v[74:75], v[134:135], v[196:197]
	global_store_dwordx4 v214, v[72:75], s[10:11] offset:64
	s_waitcnt vmcnt(31)
	v_lshlrev_b32_e32 v160, 16, v198
	v_and_b32_e32 v161, 0xffff0000, v198
	v_lshlrev_b32_e32 v198, 16, v199
	v_and_b32_e32 v199, 0xffff0000, v199
	v_pk_fma_f32 v[68:69], v[68:69], v[136:137], v[160:161]
	v_pk_fma_f32 v[70:71], v[70:71], v[138:139], v[198:199]
	global_store_dwordx4 v214, v[68:71], s[10:11] offset:512
	s_waitcnt vmcnt(31)
	v_lshlrev_b32_e32 v160, 16, v200
	v_and_b32_e32 v161, 0xffff0000, v200
	v_lshlrev_b32_e32 v200, 16, v201
	v_and_b32_e32 v201, 0xffff0000, v201
	v_pk_fma_f32 v[64:65], v[64:65], v[140:141], v[160:161]
	v_pk_fma_f32 v[66:67], v[66:67], v[142:143], v[200:201]
	global_store_dwordx4 v214, v[64:67], s[10:11] offset:576
	s_waitcnt vmcnt(31)
	v_lshlrev_b32_e32 v160, 16, v202
	v_and_b32_e32 v161, 0xffff0000, v202
	v_lshlrev_b32_e32 v202, 16, v203
	v_and_b32_e32 v203, 0xffff0000, v203
	v_pk_fma_f32 v[60:61], v[60:61], v[128:129], v[160:161]
	v_pk_fma_f32 v[62:63], v[62:63], v[130:131], v[202:203]
	v_add_u32_e32 v214, 0x80000, v211
	global_store_dwordx4 v214, v[60:63], s[10:11] offset:0
	s_waitcnt vmcnt(31)
	v_lshlrev_b32_e32 v160, 16, v204
	v_and_b32_e32 v161, 0xffff0000, v204
	v_lshlrev_b32_e32 v204, 16, v205
	v_and_b32_e32 v205, 0xffff0000, v205
	v_pk_fma_f32 v[56:57], v[56:57], v[132:133], v[160:161]
	v_pk_fma_f32 v[58:59], v[58:59], v[134:135], v[204:205]
	global_store_dwordx4 v214, v[56:59], s[10:11] offset:64
	s_waitcnt vmcnt(31)
	v_lshlrev_b32_e32 v160, 16, v206
	v_and_b32_e32 v161, 0xffff0000, v206
	v_lshlrev_b32_e32 v206, 16, v207
	v_and_b32_e32 v207, 0xffff0000, v207
	v_pk_fma_f32 v[52:53], v[52:53], v[136:137], v[160:161]
	v_pk_fma_f32 v[54:55], v[54:55], v[138:139], v[206:207]
	global_store_dwordx4 v214, v[52:55], s[10:11] offset:512
	s_waitcnt vmcnt(31)
	v_lshlrev_b32_e32 v160, 16, v208
	v_and_b32_e32 v161, 0xffff0000, v208
	v_lshlrev_b32_e32 v208, 16, v209
	v_and_b32_e32 v209, 0xffff0000, v209
	v_pk_fma_f32 v[48:49], v[48:49], v[140:141], v[160:161]
	v_pk_fma_f32 v[50:51], v[50:51], v[142:143], v[208:209]
	global_store_dwordx4 v214, v[48:51], s[10:11] offset:576
	s_waitcnt vmcnt(30)
; __device__ __forceinline__ unsigned cvt_pk_bf16(float lo, float hi) { unsigned r; asm volatile("v_cvt_pk_bf16_f32 %0, %1, %2" : "=v"(r) : "v"(lo), "v"(hi)); return r; }
;     __device__ __forceinline__ void operator()(const f32x4 (&acc)[2][2][4][2], const Unit& u, int wr, int wc, int fr, int fq) const {
;         int row0 = u.pm * BM + wr * 64 + fr + row_off; const bool isctx = row0 >= NLAT; const int b = isctx ? 8 : (row0 >> 12);
;         const void* bp = isctx ? base_ctx : base_lat; void* op = isctx ? out_ctx : out_lat; if (isctx) row0 -= NLAT;
;         const int col0 = u.pn * BM + wc * 32 + 4 * fq;
;         f32x4 gv[2][2];
; #pragma unroll
;         for (int bj = 0; bj < 2; ++bj)
; #pragma unroll
;             for (int n = 0; n < 2; ++n) gv[bj][n] = *(const f32x4*)(gate + b * MODS + col0 + bj * HALF + n * 16);
; #pragma unroll
;         for (int ai = 0; ai < 2; ++ai)
; #pragma unroll
;             for (int m = 0; m < 4; ++m) { const size_t off = (size_t)(row0 + ai * HALF + m * 16) * DM + col0;
; #pragma unroll
;                 for (int bj = 0; bj < 2; ++bj)
; #pragma unroll
;                     for (int n = 0; n < 2; ++n) { const size_t o2 = off + bj * HALF + n * 16; f32x4 bs;
;                         if (BB) { const u32x2 r = *(const u32x2*)((const bf16_t*)bp + o2); bs = (f32x4){__uint_as_float(r.x << 16), __uint_as_float(r.x & 0xffff0000u), __uint_as_float(r.y << 16), __uint_as_float(r.y & 0xffff0000u)}; }
;                         else bs = *(const f32x4*)((const float*)bp + o2);
;                         const f32x4 o = bs + gv[bj][n] * acc[ai][bj][m][n];
;                         if (OB) { u32x2 w; w.x = cvt_pk_bf16(o[0], o[1]); w.y = cvt_pk_bf16(o[2], o[3]); *(u32x2*)((bf16_t*)op + o2) = w; }
;                         else *(f32x4*)((float*)op + o2) = o; } }
;     }
	v_lshlrev_b32_e32 v160, 16, v162
	v_and_b32_e32 v161, 0xffff0000, v162
	v_lshlrev_b32_e32 v162, 16, v163
	v_and_b32_e32 v163, 0xffff0000, v163
	v_pk_fma_f32 v[44:45], v[44:45], v[128:129], v[160:161]
	v_pk_fma_f32 v[46:47], v[46:47], v[130:131], v[162:163]
	v_add_u32_e32 v214, 0x90000, v211
	global_store_dwordx4 v214, v[44:47], s[10:11] offset:0
	s_waitcnt vmcnt(29)
	v_lshlrev_b32_e32 v160, 16, v172
	v_and_b32_e32 v161, 0xffff0000, v172
	v_lshlrev_b32_e32 v172, 16, v173
	v_and_b32_e32 v173, 0xffff0000, v173
	v_pk_fma_f32 v[40:41], v[40:41], v[132:133], v[160:161]
	v_pk_fma_f32 v[42:43], v[42:43], v[134:135], v[172:173]
	global_store_dwordx4 v214, v[40:43], s[10:11] offset:64
	s_waitcnt vmcnt(29)
	v_lshlrev_b32_e32 v160, 16, v124
	v_and_b32_e32 v161, 0xffff0000, v124
	v_lshlrev_b32_e32 v124, 16, v125
	v_and_b32_e32 v125, 0xffff0000, v125
	v_pk_fma_f32 v[36:37], v[36:37], v[136:137], v[160:161]
	v_pk_fma_f32 v[38:39], v[38:39], v[138:139], v[124:125]
	global_store_dwordx4 v214, v[36:39], s[10:11] offset:512
	s_waitcnt vmcnt(29)
	v_lshlrev_b32_e32 v160, 16, v126
	v_and_b32_e32 v161, 0xffff0000, v126
	v_lshlrev_b32_e32 v126, 16, v127
	v_and_b32_e32 v127, 0xffff0000, v127
	v_pk_fma_f32 v[32:33], v[32:33], v[140:141], v[160:161]
	v_pk_fma_f32 v[34:35], v[34:35], v[142:143], v[126:127]
	global_store_dwordx4 v214, v[32:35], s[10:11] offset:576
	s_waitcnt vmcnt(28)
	v_lshlrev_b32_e32 v160, 16, v174
	v_and_b32_e32 v161, 0xffff0000, v174
	v_lshlrev_b32_e32 v174, 16, v175
	v_and_b32_e32 v175, 0xffff0000, v175
	v_pk_fma_f32 v[28:29], v[28:29], v[128:129], v[160:161]
	v_pk_fma_f32 v[30:31], v[30:31], v[130:131], v[174:175]
	v_add_u32_e32 v214, 0xa0000, v211
	global_store_dwordx4 v214, v[28:31], s[10:11] offset:0
	s_waitcnt vmcnt(28)
	v_lshlrev_b32_e32 v160, 16, v120
	v_and_b32_e32 v161, 0xffff0000, v120
	v_lshlrev_b32_e32 v120, 16, v121
	v_and_b32_e32 v121, 0xffff0000, v121
	v_pk_fma_f32 v[24:25], v[24:25], v[132:133], v[160:161]
	v_pk_fma_f32 v[26:27], v[26:27], v[134:135], v[120:121]
	global_store_dwordx4 v214, v[24:27], s[10:11] offset:64
	s_waitcnt vmcnt(28)
	v_lshlrev_b32_e32 v160, 16, v122
	v_and_b32_e32 v161, 0xffff0000, v122
	v_lshlrev_b32_e32 v122, 16, v123
	v_and_b32_e32 v123, 0xffff0000, v123
	v_pk_fma_f32 v[20:21], v[20:21], v[136:137], v[160:161]
	v_pk_fma_f32 v[22:23], v[22:23], v[138:139], v[122:123]
	global_store_dwordx4 v214, v[20:23], s[10:11] offset:512
	s_waitcnt vmcnt(27)
	v_lshlrev_b32_e32 v160, 16, v176
	v_and_b32_e32 v161, 0xffff0000, v176
	v_lshlrev_b32_e32 v176, 16, v177
	v_and_b32_e32 v177, 0xffff0000, v177
	v_pk_fma_f32 v[16:17], v[16:17], v[140:141], v[160:161]
	v_pk_fma_f32 v[18:19], v[18:19], v[142:143], v[176:177]
	global_store_dwordx4 v214, v[16:19], s[10:11] offset:576
	s_waitcnt vmcnt(27)
	v_lshlrev_b32_e32 v160, 16, v116
	v_and_b32_e32 v161, 0xffff0000, v116
	v_lshlrev_b32_e32 v116, 16, v117
	v_and_b32_e32 v117, 0xffff0000, v117
	v_pk_fma_f32 v[12:13], v[12:13], v[128:129], v[160:161]
	v_pk_fma_f32 v[14:15], v[14:15], v[130:131], v[116:117]
	v_add_u32_e32 v214, 0xb0000, v211
	global_store_dwordx4 v214, v[12:15], s[10:11] offset:0
	s_waitcnt vmcnt(27)
	v_lshlrev_b32_e32 v160, 16, v118
	v_and_b32_e32 v161, 0xffff0000, v118
	v_lshlrev_b32_e32 v118, 16, v119
	v_and_b32_e32 v119, 0xffff0000, v119
	v_pk_fma_f32 v[8:9], v[8:9], v[132:133], v[160:161]
	v_pk_fma_f32 v[10:11], v[10:11], v[134:135], v[118:119]
	global_store_dwordx4 v214, v[8:11], s[10:11] offset:64
	s_waitcnt vmcnt(26)
	v_lshlrev_b32_e32 v160, 16, v178
	v_and_b32_e32 v161, 0xffff0000, v178
	v_lshlrev_b32_e32 v178, 16, v179
	v_and_b32_e32 v179, 0xffff0000, v179
	v_pk_fma_f32 v[4:5], v[4:5], v[136:137], v[160:161]
	v_pk_fma_f32 v[6:7], v[6:7], v[138:139], v[178:179]
	global_store_dwordx4 v214, v[4:7], s[10:11] offset:512
	s_waitcnt vmcnt(26)
	v_lshlrev_b32_e32 v160, 16, v112
	v_and_b32_e32 v161, 0xffff0000, v112
	v_lshlrev_b32_e32 v112, 16, v113
	v_and_b32_e32 v113, 0xffff0000, v113
	v_pk_fma_f32 v[0:1], v[0:1], v[140:141], v[160:161]
	v_pk_fma_f32 v[2:3], v[2:3], v[142:143], v[112:113]
	global_store_dwordx4 v214, v[0:3], s[10:11] offset:576
	s_and_b64 vcc, exec, s[0:1]
	s_mov_b64 s[0:1], -1
	s_cbranch_vccnz .LBB0_1884
	s_andn2_b64 vcc, exec, s[12:13]
	s_cbranch_vccnz .LBB0_1883
	s_barrier
	s_branch .LBB0_1883
